# baseline (speedup 1.0000x reference)
; DI int my_block() { int b = blockIdx.x; asm volatile("" : "+s"(b)); return b; }
; #define G_STAGE(bufoff, gbase, voff) do { _Pragma("unroll") for (int _i = 0; _i < 2; ++_i) \
;         __builtin_amdgcn_global_load_lds((const unsigned*)((const char*)(gbase) + (voff)[_i]), (LAS unsigned*)(lds + (bufoff) + ldsw + _i * 8192), 16, 0, 0); } while (0)
; #define G_LDA(dst, b, h) do { _Pragma("unroll") for (int m = 0; m < 4; ++m) _Pragma("unroll") for (int k = 0; k < 2; ++k) dst[m][k] = *(const LAS bf16x8*)(lds + G_SA(b, h) + aoff + m * 2048 + k * 1024); } while (0)
; #define G_LDB(dst, b, h) do { _Pragma("unroll") for (int n = 0; n < 2; ++n) _Pragma("unroll") for (int k = 0; k < 2; ++k) dst[n][k] = *(const LAS bf16x8*)(lds + G_SB(b, h) + boff + n * 2048 + k * 1024); } while (0)
; #define G_BAR __builtin_amdgcn_s_barrier()
; template <class J>
; DI void gemm_phase(LAS unsigned char* lds, const J& job) {
;     ...
;   f32x4 acc[2][2][4][2];
; #pragma unroll
;   for (int a = 0; a < 2; ++a)
; #pragma unroll
;     for (int b = 0; b < 2; ++b)
; #pragma unroll
;       for (int m = 0; m < 4; ++m)
; #pragma unroll
;         for (int n = 0; n < 2; ++n) acc[a][b][m][n] = (f32x4){0.f, 0.f, 0.f, 0.f};
;   bf16x8 At[4][2], B0[2][2], B1[2][2];
;   const char* cA = job.aptr(cur); const char* cB = job.bptr(cur);
;   const int koff = (my_block() & 7) * (nt >> 3), kmask = nt - 1;
;     ...
;   G_STAGE(G_SB(0, 0), cB + G_KT(0), voffB); G_STAGE(G_SA(0, 0), cA + G_KT(0), voffA); G_STAGE(G_SB(0, 1), cB + hstepB + G_KT(0), voffB); G_STAGE(G_SA(0, 1), cA + hstepA + G_KT(0), voffA);
;   if (wr == 1) G_BAR;
;   G_WAIT_V(4); G_BAR;
;   G_STAGE(G_SB(1, 0), cB + G_KT(1), voffB); G_STAGE(G_SA(1, 0), cA + G_KT(1), voffA); G_STAGE(G_SB(1, 1), cB + hstepB + G_KT(1), voffB);
;   G_WAIT_V(6); G_BAR;
;   for (;;) {
;     const bool has_next = job.next(ui + 1, nxt);
;     const char* nA = has_next ? job.aptr(nxt) : cA; const char* nB = has_next ? job.bptr(nxt) : cB;
;     for (int t = 0; t < nt; t += 2) {
;       const bool last = (t == nt - 2);
;       const char* a1 = cA + G_KT(t + 1);
;       const char* a2 = last ? nA + G_KT(0) : cA + G_KT(t + 2); const char* b2 = last ? nB + G_KT(0) : cB + G_KT(t + 2);
;       const char* a3 = last ? nA + G_KT(1) : cA + G_KT(t + 3); const char* b3 = last ? nB + G_KT(1) : cB + G_KT(t + 3);
;       G_LDB(B0, 0, 0); G_SCHED; G_LDA(At, 0, 0); G_STAGE(G_SA(1, 1), a1 + hstepA, voffA);
.LBB0_41:
	s_ashr_i32 s21, s20, 31
	s_lshl_b64 s[0:1], s[20:21], 20
	s_add_u32 s62, s10, s0
	s_addc_u32 s63, s11, s1
	s_ashr_i32 s23, s22, 31
	s_lshl_b64 s[0:1], s[22:23], 20
	s_add_u32 s64, s12, s0
	s_addc_u32 s65, s13, s1
	s_add_u32 s21, s70, 0x80000
	s_addc_u32 s23, s71, 0
	s_and_b64 s[0:1], s[72:73], exec
	s_cselect_b32 s4, s62, s70
	s_cselect_b32 s0, s65, s69
	s_cselect_b32 s1, s64, s68
	s_cselect_b32 s2, s63, s71
	s_add_u32 s47, s4, s24
	s_addc_u32 vcc_lo, s2, 0
	s_add_u32 vcc_hi, s1, s24
	s_addc_u32 s33, s0, 0
	s_add_u32 s97, s4, s86
	s_addc_u32 s4, s2, 0
	s_add_u32 s5, s1, s86
	v_mov_b32_e32 v0, 0
	s_addc_u32 s6, s0, 0
	s_mov_b32 s7, -2
	s_mov_b32 s44, s56
	s_mov_b32 s57, s96
	v_mov_b32_e32 v1, v0
	v_mov_b32_e32 v2, v0
	v_mov_b32_e32 v3, v0
	v_mov_b32_e32 v4, v0
	v_mov_b32_e32 v5, v0
	v_mov_b32_e32 v6, v0
	v_mov_b32_e32 v7, v0
	v_mov_b32_e32 v8, v0
	v_mov_b32_e32 v9, v0
	v_mov_b32_e32 v10, v0
	v_mov_b32_e32 v11, v0
	v_mov_b32_e32 v16, v0
	v_mov_b32_e32 v17, v0
	v_mov_b32_e32 v18, v0
	v_mov_b32_e32 v19, v0
	v_mov_b32_e32 v32, v0
	v_mov_b32_e32 v33, v0
	v_mov_b32_e32 v34, v0
	v_mov_b32_e32 v35, v0
	v_mov_b32_e32 v36, v0
	v_mov_b32_e32 v37, v0
	v_mov_b32_e32 v38, v0
	v_mov_b32_e32 v39, v0
	v_mov_b32_e32 v48, v0
	v_mov_b32_e32 v49, v0
	v_mov_b32_e32 v50, v0
	v_mov_b32_e32 v51, v0
	v_mov_b32_e32 v52, v0
	v_mov_b32_e32 v53, v0
	v_mov_b32_e32 v54, v0
	v_mov_b32_e32 v55, v0
	v_mov_b32_e32 v12, v0
	v_mov_b32_e32 v13, v0
	v_mov_b32_e32 v14, v0
	v_mov_b32_e32 v15, v0
	v_mov_b32_e32 v20, v0
	v_mov_b32_e32 v21, v0
	v_mov_b32_e32 v22, v0
	v_mov_b32_e32 v23, v0
	v_mov_b32_e32 v24, v0
	v_mov_b32_e32 v25, v0
	v_mov_b32_e32 v26, v0
	v_mov_b32_e32 v27, v0
	v_mov_b32_e32 v28, v0
	v_mov_b32_e32 v29, v0
	v_mov_b32_e32 v30, v0
	v_mov_b32_e32 v31, v0
	v_mov_b32_e32 v40, v0
	v_mov_b32_e32 v41, v0
	v_mov_b32_e32 v42, v0
	v_mov_b32_e32 v43, v0
	v_mov_b32_e32 v44, v0
	v_mov_b32_e32 v45, v0
	v_mov_b32_e32 v46, v0
	v_mov_b32_e32 v47, v0
	v_mov_b32_e32 v56, v0
	v_mov_b32_e32 v57, v0
	v_mov_b32_e32 v58, v0
	v_mov_b32_e32 v59, v0
	v_mov_b32_e32 v60, v0
	v_mov_b32_e32 v61, v0
	v_mov_b32_e32 v62, v0
	v_mov_b32_e32 v63, v0
	v_mov_b32_e32 v64, v0
	v_mov_b32_e32 v65, v0
	v_mov_b32_e32 v66, v0
	v_mov_b32_e32 v67, v0
	v_mov_b32_e32 v68, v0
	v_mov_b32_e32 v69, v0
	v_mov_b32_e32 v70, v0
	v_mov_b32_e32 v71, v0
	v_mov_b32_e32 v80, v0
	v_mov_b32_e32 v81, v0
	v_mov_b32_e32 v82, v0
	v_mov_b32_e32 v83, v0
	v_mov_b32_e32 v84, v0
	v_mov_b32_e32 v85, v0
	v_mov_b32_e32 v86, v0
	v_mov_b32_e32 v87, v0
	v_mov_b32_e32 v96, v0
	v_mov_b32_e32 v97, v0
	v_mov_b32_e32 v98, v0
	v_mov_b32_e32 v99, v0
	v_mov_b32_e32 v100, v0
	v_mov_b32_e32 v101, v0
	v_mov_b32_e32 v102, v0
	v_mov_b32_e32 v103, v0
	v_mov_b32_e32 v112, v0
	v_mov_b32_e32 v113, v0
	v_mov_b32_e32 v114, v0
	v_mov_b32_e32 v115, v0
	v_mov_b32_e32 v116, v0
	v_mov_b32_e32 v117, v0
	v_mov_b32_e32 v118, v0
	v_mov_b32_e32 v119, v0
	v_mov_b32_e32 v72, v0
	v_mov_b32_e32 v73, v0
	v_mov_b32_e32 v74, v0
	v_mov_b32_e32 v75, v0
	v_mov_b32_e32 v76, v0
	v_mov_b32_e32 v77, v0
	v_mov_b32_e32 v78, v0
	v_mov_b32_e32 v79, v0
	v_mov_b32_e32 v88, v0
	v_mov_b32_e32 v89, v0
	v_mov_b32_e32 v90, v0
	v_mov_b32_e32 v91, v0
	v_mov_b32_e32 v92, v0
	v_mov_b32_e32 v93, v0
	v_mov_b32_e32 v94, v0
	v_mov_b32_e32 v95, v0
	v_mov_b32_e32 v104, v0
	v_mov_b32_e32 v105, v0
	v_mov_b32_e32 v106, v0
	v_mov_b32_e32 v107, v0
	v_mov_b32_e32 v108, v0
	v_mov_b32_e32 v109, v0
	v_mov_b32_e32 v110, v0
	v_mov_b32_e32 v111, v0
	v_mov_b32_e32 v120, v0
	v_mov_b32_e32 v121, v0
	v_mov_b32_e32 v122, v0
	v_mov_b32_e32 v123, v0
	v_mov_b32_e32 v124, v0
	v_mov_b32_e32 v125, v0
	v_mov_b32_e32 v126, v0
	v_mov_b32_e32 v127, v0
	s_add_i32 s1, s57, 0xffffff80
	s_and_b32 s0, s44, 0xf80
	s_and_b32 s1, s1, 0xf00
	s_add_u32 s2, s70, s1
	s_addc_u32 s72, s71, 0
	s_add_u32 s1, s68, s1
	s_addc_u32 s73, s69, 0
	s_and_b32 s74, s57, 0xf80
	s_add_u32 s80, s70, s74
	s_addc_u32 s75, s71, 0
	s_add_u32 s54, s68, s74
	s_addc_u32 s55, s69, 0
	s_cmp_eq_u32 s7, 28
	s_cselect_b32 s77, vcc_lo, s72
	s_cselect_b32 s76, s47, s2
	s_cselect_b32 s79, s33, s73
	s_cselect_b32 s78, vcc_hi, s1
	s_cselect_b32 s75, s4, s75
	s_cselect_b32 s74, s97, s80
	s_cselect_b32 s73, s6, s55
	s_cselect_b32 s72, s5, s54
.LBB0_42:
	s_add_i32 s2, s84, 0x100
	v_add_u32_e32 v140, s2, v162
	ds_read_b128 v[128:131], v140
	ds_read_b128 v[132:135], v140 offset:1024
	ds_read_b128 v[136:139], v140 offset:2048
	ds_read_b128 v[140:143], v140 offset:3072
	s_add_u32 s0, s21, s0
	s_addc_u32 s1, s23, 0
	v_lshl_add_u64 v[158:159], s[0:1], 0, v[148:149]
	s_add_i32 m0, s25, 0xc000
	ds_read_b128 v[154:157], v163
	ds_read_b128 v[164:167], v163 offset:1024
	ds_read_b128 v[168:171], v163 offset:2048
	ds_read_b128 v[172:175], v163 offset:3072
	ds_read_b128 v[176:179], v163 offset:4096
	ds_read_b128 v[180:183], v163 offset:5120
	ds_read_b128 v[184:187], v163 offset:6144
	ds_read_b128 v[188:191], v163 offset:7168
	global_load_lds_dwordx4 v[158:159], off
	v_lshl_add_u64 v[158:159], s[0:1], 0, v[150:151]
	s_add_i32 m0, s25, 0xe000
	s_nop 0
	global_load_lds_dwordx4 v[158:159], off
	s_waitcnt lgkmcnt(8)
	s_barrier
; #define G_STAGE(bufoff, gbase, voff) do { _Pragma("unroll") for (int _i = 0; _i < 2; ++_i) \
;         __builtin_amdgcn_global_load_lds((const unsigned*)((const char*)(gbase) + (voff)[_i]), (LAS unsigned*)(lds + (bufoff) + ldsw + _i * 8192), 16, 0, 0); } while (0)
; #define G_LDA(dst, b, h) do { _Pragma("unroll") for (int m = 0; m < 4; ++m) _Pragma("unroll") for (int k = 0; k < 2; ++k) dst[m][k] = *(const LAS bf16x8*)(lds + G_SA(b, h) + aoff + m * 2048 + k * 1024); } while (0)
; #define G_LDB(dst, b, h) do { _Pragma("unroll") for (int n = 0; n < 2; ++n) _Pragma("unroll") for (int k = 0; k < 2; ++k) dst[n][k] = *(const LAS bf16x8*)(lds + G_SB(b, h) + boff + n * 2048 + k * 1024); } while (0)
; #define G_MMA(ai, bj, At, Bt) do { __builtin_amdgcn_s_setprio(1); _Pragma("unroll") for (int m = 0; m < 4; ++m) _Pragma("unroll") for (int n = 0; n < 2; ++n) _Pragma("unroll") for (int k = 0; k < 2; ++k) \
;         acc[ai][bj][m][n] = __builtin_amdgcn_mfma_f32_16x16x32_bf16(Bt[n][k], At[m][k], acc[ai][bj][m][n], 0, 0, 0); __builtin_amdgcn_s_setprio(0); } while (0)
; #define G_WAIT_V(n) asm volatile("s_waitcnt vmcnt(" #n ")" ::: "memory")
; #define G_WAIT_L(n) asm volatile("s_waitcnt lgkmcnt(" #n ")" ::: "memory")
; #define G_BAR __builtin_amdgcn_s_barrier()
; #define G_SCHED __builtin_amdgcn_sched_barrier(0)
; template <class J>
; DI void gemm_phase(LAS unsigned char* lds, const J& job) {
;     ...
;       G_WAIT_L(8); G_BAR; G_WAIT_L(0); G_MMA(0, 0, At, B0); G_BAR; G_SCHED;
;       G_LDB(B1, 0, 1); G_STAGE(G_SB(0, 0), b2, voffB);
;       G_BAR; G_WAIT_L(0); G_MMA(0, 1, At, B1); G_BAR;
;       G_LDA(At, 0, 1); G_STAGE(G_SA(0, 0), a2, voffA);
;       G_BAR; G_WAIT_L(0); G_MMA(1, 0, At, B0); G_BAR; G_SCHED;
;       G_STAGE(G_SB(0, 1), b2 + hstepB, voffB);
;       G_WAIT_V(6); G_BAR; G_MMA(1, 1, At, B1); G_BAR;
	s_waitcnt lgkmcnt(0)
	s_setprio 1
	s_waitcnt lgkmcnt(0)
	v_mfma_f32_16x16x32_bf16 v[124:127], v[128:131], v[154:157], v[124:127]
	v_mfma_f32_16x16x32_bf16 v[120:123], v[136:139], v[154:157], v[120:123]
	v_mfma_f32_16x16x32_bf16 v[108:111], v[128:131], v[168:171], v[108:111]
	v_mfma_f32_16x16x32_bf16 v[104:107], v[136:139], v[168:171], v[104:107]
	v_mfma_f32_16x16x32_bf16 v[92:95], v[128:131], v[176:179], v[92:95]
	v_mfma_f32_16x16x32_bf16 v[88:91], v[136:139], v[176:179], v[88:91]
	v_mfma_f32_16x16x32_bf16 v[76:79], v[128:131], v[184:187], v[76:79]
	v_mfma_f32_16x16x32_bf16 v[72:75], v[136:139], v[184:187], v[72:75]
	v_mfma_f32_16x16x32_bf16 v[124:127], v[132:135], v[164:167], v[124:127]
	v_mfma_f32_16x16x32_bf16 v[120:123], v[140:143], v[164:167], v[120:123]
	v_mfma_f32_16x16x32_bf16 v[108:111], v[132:135], v[172:175], v[108:111]
	v_mfma_f32_16x16x32_bf16 v[104:107], v[140:143], v[172:175], v[104:107]
	v_mfma_f32_16x16x32_bf16 v[92:95], v[132:135], v[180:183], v[92:95]
	v_mfma_f32_16x16x32_bf16 v[88:91], v[140:143], v[180:183], v[88:91]
	v_mfma_f32_16x16x32_bf16 v[76:79], v[132:135], v[188:191], v[76:79]
	v_mfma_f32_16x16x32_bf16 v[72:75], v[140:143], v[188:191], v[72:75]
	s_setprio 0
	s_barrier
	s_add_i32 s54, s85, 0x100
	v_add_u32_e32 v158, s54, v162
	s_add_i32 s0, s2, s14
	ds_read_b128 v[192:195], v158
	ds_read_b128 v[196:199], v158 offset:1024
	ds_read_b128 v[200:203], v158 offset:2048
	ds_read_b128 v[204:207], v158 offset:3072
	v_lshl_add_u64 v[158:159], s[78:79], 0, v[146:147]
	s_mov_b32 m0, s0
	s_nop 0
	global_load_lds_dwordx4 v[158:159], off
	v_lshl_add_u64 v[158:159], s[78:79], 0, v[152:153]
	s_add_i32 m0, s0, 0x2000
	s_nop 0
	global_load_lds_dwordx4 v[158:159], off
	s_barrier
	s_waitcnt lgkmcnt(0)
	s_setprio 1
	s_waitcnt lgkmcnt(0)
	v_mfma_f32_16x16x32_bf16 v[116:119], v[192:195], v[154:157], v[116:119]
	v_mfma_f32_16x16x32_bf16 v[112:115], v[200:203], v[154:157], v[112:115]
	v_mfma_f32_16x16x32_bf16 v[100:103], v[192:195], v[168:171], v[100:103]
	v_mfma_f32_16x16x32_bf16 v[96:99], v[200:203], v[168:171], v[96:99]
	v_mfma_f32_16x16x32_bf16 v[84:87], v[192:195], v[176:179], v[84:87]
	v_mfma_f32_16x16x32_bf16 v[80:83], v[200:203], v[176:179], v[80:83]
	v_mfma_f32_16x16x32_bf16 v[68:71], v[192:195], v[184:187], v[68:71]
	v_mfma_f32_16x16x32_bf16 v[64:67], v[200:203], v[184:187], v[64:67]
	v_mfma_f32_16x16x32_bf16 v[116:119], v[196:199], v[164:167], v[116:119]
	v_mfma_f32_16x16x32_bf16 v[112:115], v[204:207], v[164:167], v[112:115]
	v_mfma_f32_16x16x32_bf16 v[100:103], v[196:199], v[172:175], v[100:103]
	v_mfma_f32_16x16x32_bf16 v[96:99], v[204:207], v[172:175], v[96:99]
	v_mfma_f32_16x16x32_bf16 v[84:87], v[196:199], v[180:183], v[84:87]
	v_mfma_f32_16x16x32_bf16 v[80:83], v[204:207], v[180:183], v[80:83]
	v_mfma_f32_16x16x32_bf16 v[68:71], v[196:199], v[188:191], v[68:71]
	v_mfma_f32_16x16x32_bf16 v[64:67], v[204:207], v[188:191], v[64:67]
	s_setprio 0
	s_mov_b32 m0, s25
	v_lshl_add_u64 v[158:159], s[76:77], 0, v[148:149]
	s_barrier
	ds_read_b128 v[154:157], v163 offset:16384
	ds_read_b128 v[164:167], v163 offset:17408
	ds_read_b128 v[168:171], v163 offset:18432
	ds_read_b128 v[172:175], v163 offset:19456
	ds_read_b128 v[176:179], v163 offset:20480
	ds_read_b128 v[180:183], v163 offset:21504
	ds_read_b128 v[184:187], v163 offset:22528
	ds_read_b128 v[188:191], v163 offset:23552
	global_load_lds_dwordx4 v[158:159], off
	v_lshl_add_u64 v[158:159], s[76:77], 0, v[150:151]
	s_mov_b32 m0, s36
	s_nop 0
	global_load_lds_dwordx4 v[158:159], off
	s_barrier
	s_waitcnt lgkmcnt(0)
	s_setprio 1
	s_waitcnt lgkmcnt(0)
	v_mfma_f32_16x16x32_bf16 v[60:63], v[128:131], v[154:157], v[60:63]
	v_mfma_f32_16x16x32_bf16 v[56:59], v[136:139], v[154:157], v[56:59]
	v_mfma_f32_16x16x32_bf16 v[44:47], v[128:131], v[168:171], v[44:47]
	v_mfma_f32_16x16x32_bf16 v[40:43], v[136:139], v[168:171], v[40:43]
	v_mfma_f32_16x16x32_bf16 v[28:31], v[128:131], v[176:179], v[28:31]
	v_mfma_f32_16x16x32_bf16 v[24:27], v[136:139], v[176:179], v[24:27]
	v_mfma_f32_16x16x32_bf16 v[20:23], v[128:131], v[184:187], v[20:23]
	v_mfma_f32_16x16x32_bf16 v[12:15], v[136:139], v[184:187], v[12:15]
	v_mfma_f32_16x16x32_bf16 v[60:63], v[132:135], v[164:167], v[60:63]
	v_mfma_f32_16x16x32_bf16 v[56:59], v[140:143], v[164:167], v[56:59]
	v_mfma_f32_16x16x32_bf16 v[44:47], v[132:135], v[172:175], v[44:47]
	v_mfma_f32_16x16x32_bf16 v[40:43], v[140:143], v[172:175], v[40:43]
	v_mfma_f32_16x16x32_bf16 v[28:31], v[132:135], v[180:183], v[28:31]
	v_mfma_f32_16x16x32_bf16 v[24:27], v[140:143], v[180:183], v[24:27]
	v_mfma_f32_16x16x32_bf16 v[20:23], v[132:135], v[188:191], v[20:23]
	v_mfma_f32_16x16x32_bf16 v[12:15], v[140:143], v[188:191], v[12:15]
	s_setprio 0
	s_barrier
	s_add_u32 s0, s78, 0x80000
	s_addc_u32 s1, s79, 0
	s_add_i32 s2, s54, s14
	v_lshl_add_u64 v[128:129], s[0:1], 0, v[146:147]
	s_mov_b32 m0, s2
	s_nop 0
	global_load_lds_dwordx4 v[128:129], off
	v_lshl_add_u64 v[128:129], s[0:1], 0, v[152:153]
	s_add_i32 m0, s2, 0x2000
	s_nop 0
	global_load_lds_dwordx4 v[128:129], off
	s_waitcnt vmcnt(6)
	s_barrier
; #define G_STAGE(bufoff, gbase, voff) do { _Pragma("unroll") for (int _i = 0; _i < 2; ++_i) \
;         __builtin_amdgcn_global_load_lds((const unsigned*)((const char*)(gbase) + (voff)[_i]), (LAS unsigned*)(lds + (bufoff) + ldsw + _i * 8192), 16, 0, 0); } while (0)
; #define G_LDA(dst, b, h) do { _Pragma("unroll") for (int m = 0; m < 4; ++m) _Pragma("unroll") for (int k = 0; k < 2; ++k) dst[m][k] = *(const LAS bf16x8*)(lds + G_SA(b, h) + aoff + m * 2048 + k * 1024); } while (0)
; #define G_LDB(dst, b, h) do { _Pragma("unroll") for (int n = 0; n < 2; ++n) _Pragma("unroll") for (int k = 0; k < 2; ++k) dst[n][k] = *(const LAS bf16x8*)(lds + G_SB(b, h) + boff + n * 2048 + k * 1024); } while (0)
; #define G_MMA(ai, bj, At, Bt) do { __builtin_amdgcn_s_setprio(1); _Pragma("unroll") for (int m = 0; m < 4; ++m) _Pragma("unroll") for (int n = 0; n < 2; ++n) _Pragma("unroll") for (int k = 0; k < 2; ++k) \
;         acc[ai][bj][m][n] = __builtin_amdgcn_mfma_f32_16x16x32_bf16(Bt[n][k], At[m][k], acc[ai][bj][m][n], 0, 0, 0); __builtin_amdgcn_s_setprio(0); } while (0)
; #define G_WAIT_V(n) asm volatile("s_waitcnt vmcnt(" #n ")" ::: "memory")
; #define G_WAIT_L(n) asm volatile("s_waitcnt lgkmcnt(" #n ")" ::: "memory")
; #define G_BAR __builtin_amdgcn_s_barrier()
; #define G_SCHED __builtin_amdgcn_sched_barrier(0)
; template <class J>
; DI void gemm_phase(LAS unsigned char* lds, const J& job) {
;     ...
;       G_WAIT_V(6); G_BAR; G_MMA(1, 1, At, B1); G_BAR;
;       G_LDB(B0, 1, 0); G_SCHED; G_LDA(At, 1, 0); G_STAGE(G_SA(0, 1), a2 + hstepA, voffA);
;       G_WAIT_L(8); G_BAR; G_WAIT_L(0); G_MMA(0, 0, At, B0); G_BAR; G_SCHED;
;       G_LDB(B1, 1, 1); G_STAGE(G_SB(1, 0), b3, voffB);
;       G_BAR; G_WAIT_L(0); G_MMA(0, 1, At, B1); G_BAR;
;       G_LDA(At, 1, 1); G_STAGE(G_SA(1, 0), a3, voffA);
;       G_BAR; G_WAIT_L(0); G_MMA(1, 0, At, B0); G_BAR; G_SCHED;
	s_setprio 1
	v_mfma_f32_16x16x32_bf16 v[52:55], v[192:195], v[154:157], v[52:55]
	v_mfma_f32_16x16x32_bf16 v[48:51], v[200:203], v[154:157], v[48:51]
	v_mfma_f32_16x16x32_bf16 v[36:39], v[192:195], v[168:171], v[36:39]
	v_mfma_f32_16x16x32_bf16 v[32:35], v[200:203], v[168:171], v[32:35]
	v_mfma_f32_16x16x32_bf16 v[16:19], v[192:195], v[176:179], v[16:19]
	v_mfma_f32_16x16x32_bf16 v[8:11], v[200:203], v[176:179], v[8:11]
	v_mfma_f32_16x16x32_bf16 v[4:7], v[192:195], v[184:187], v[4:7]
	v_mfma_f32_16x16x32_bf16 v[0:3], v[200:203], v[184:187], v[0:3]
	v_mfma_f32_16x16x32_bf16 v[52:55], v[196:199], v[164:167], v[52:55]
	v_mfma_f32_16x16x32_bf16 v[48:51], v[204:207], v[164:167], v[48:51]
	v_mfma_f32_16x16x32_bf16 v[36:39], v[196:199], v[172:175], v[36:39]
	v_mfma_f32_16x16x32_bf16 v[32:35], v[204:207], v[172:175], v[32:35]
	v_mfma_f32_16x16x32_bf16 v[16:19], v[196:199], v[180:183], v[16:19]
	v_mfma_f32_16x16x32_bf16 v[8:11], v[204:207], v[180:183], v[8:11]
	v_mfma_f32_16x16x32_bf16 v[4:7], v[196:199], v[188:191], v[4:7]
	v_mfma_f32_16x16x32_bf16 v[0:3], v[204:207], v[188:191], v[0:3]
	s_setprio 0
	s_add_i32 s2, s88, 0x100
	v_add_u32_e32 v140, s2, v162
	s_barrier
	ds_read_b128 v[128:131], v140
	ds_read_b128 v[132:135], v140 offset:1024
	ds_read_b128 v[136:139], v140 offset:2048
	ds_read_b128 v[140:143], v140 offset:3072
	s_add_u32 s0, s76, 0x80000
	s_addc_u32 s1, s77, 0
	s_mov_b32 m0, s37
	v_lshl_add_u64 v[158:159], s[0:1], 0, v[148:149]
	ds_read_b128 v[154:157], v163 offset:32768
	ds_read_b128 v[164:167], v163 offset:33792
	ds_read_b128 v[168:171], v163 offset:34816
	ds_read_b128 v[172:175], v163 offset:35840
	ds_read_b128 v[176:179], v163 offset:36864
	ds_read_b128 v[180:183], v163 offset:37888
	ds_read_b128 v[184:187], v163 offset:38912
	ds_read_b128 v[188:191], v163 offset:39936
	global_load_lds_dwordx4 v[158:159], off
	v_lshl_add_u64 v[158:159], s[0:1], 0, v[150:151]
	s_mov_b32 m0, s38
	s_nop 0
	global_load_lds_dwordx4 v[158:159], off
	s_waitcnt lgkmcnt(8)
	s_barrier
	s_waitcnt lgkmcnt(0)
	s_setprio 1
	s_waitcnt lgkmcnt(0)
	v_mfma_f32_16x16x32_bf16 v[124:127], v[128:131], v[154:157], v[124:127]
	v_mfma_f32_16x16x32_bf16 v[120:123], v[136:139], v[154:157], v[120:123]
	v_mfma_f32_16x16x32_bf16 v[108:111], v[128:131], v[168:171], v[108:111]
	v_mfma_f32_16x16x32_bf16 v[104:107], v[136:139], v[168:171], v[104:107]
	v_mfma_f32_16x16x32_bf16 v[92:95], v[128:131], v[176:179], v[92:95]
	v_mfma_f32_16x16x32_bf16 v[88:91], v[136:139], v[176:179], v[88:91]
	v_mfma_f32_16x16x32_bf16 v[76:79], v[128:131], v[184:187], v[76:79]
	v_mfma_f32_16x16x32_bf16 v[72:75], v[136:139], v[184:187], v[72:75]
	v_mfma_f32_16x16x32_bf16 v[124:127], v[132:135], v[164:167], v[124:127]
	v_mfma_f32_16x16x32_bf16 v[120:123], v[140:143], v[164:167], v[120:123]
	v_mfma_f32_16x16x32_bf16 v[108:111], v[132:135], v[172:175], v[108:111]
	v_mfma_f32_16x16x32_bf16 v[104:107], v[140:143], v[172:175], v[104:107]
	v_mfma_f32_16x16x32_bf16 v[92:95], v[132:135], v[180:183], v[92:95]
	v_mfma_f32_16x16x32_bf16 v[88:91], v[140:143], v[180:183], v[88:91]
	v_mfma_f32_16x16x32_bf16 v[76:79], v[132:135], v[188:191], v[76:79]
	v_mfma_f32_16x16x32_bf16 v[72:75], v[140:143], v[188:191], v[72:75]
	s_setprio 0
	s_barrier
	s_add_i32 s54, s89, 0x100
	v_add_u32_e32 v158, s54, v162
	s_add_i32 s0, s2, s14
	ds_read_b128 v[192:195], v158
	ds_read_b128 v[196:199], v158 offset:1024
	ds_read_b128 v[200:203], v158 offset:2048
	ds_read_b128 v[204:207], v158 offset:3072
	v_lshl_add_u64 v[158:159], s[72:73], 0, v[146:147]
	s_mov_b32 m0, s0
	s_nop 0
	global_load_lds_dwordx4 v[158:159], off
	v_lshl_add_u64 v[158:159], s[72:73], 0, v[152:153]
	s_add_i32 m0, s0, 0x2000
	s_nop 0
	global_load_lds_dwordx4 v[158:159], off
	s_barrier
	s_waitcnt lgkmcnt(0)
	s_setprio 1
	s_waitcnt lgkmcnt(0)
	v_mfma_f32_16x16x32_bf16 v[116:119], v[192:195], v[154:157], v[116:119]
	v_mfma_f32_16x16x32_bf16 v[112:115], v[200:203], v[154:157], v[112:115]
	v_mfma_f32_16x16x32_bf16 v[100:103], v[192:195], v[168:171], v[100:103]
	v_mfma_f32_16x16x32_bf16 v[96:99], v[200:203], v[168:171], v[96:99]
	v_mfma_f32_16x16x32_bf16 v[84:87], v[192:195], v[176:179], v[84:87]
	v_mfma_f32_16x16x32_bf16 v[80:83], v[200:203], v[176:179], v[80:83]
	v_mfma_f32_16x16x32_bf16 v[68:71], v[192:195], v[184:187], v[68:71]
	v_mfma_f32_16x16x32_bf16 v[64:67], v[200:203], v[184:187], v[64:67]
	v_mfma_f32_16x16x32_bf16 v[116:119], v[196:199], v[164:167], v[116:119]
	v_mfma_f32_16x16x32_bf16 v[112:115], v[204:207], v[164:167], v[112:115]
	v_mfma_f32_16x16x32_bf16 v[100:103], v[196:199], v[172:175], v[100:103]
	v_mfma_f32_16x16x32_bf16 v[96:99], v[204:207], v[172:175], v[96:99]
	v_mfma_f32_16x16x32_bf16 v[84:87], v[196:199], v[180:183], v[84:87]
	v_mfma_f32_16x16x32_bf16 v[80:83], v[204:207], v[180:183], v[80:83]
	v_mfma_f32_16x16x32_bf16 v[68:71], v[196:199], v[188:191], v[68:71]
	v_mfma_f32_16x16x32_bf16 v[64:67], v[204:207], v[188:191], v[64:67]
	s_setprio 0
	s_mov_b32 m0, s87
	v_lshl_add_u64 v[158:159], s[74:75], 0, v[148:149]
	s_barrier
	ds_read_b128 v[154:157], v163 offset:49152
	ds_read_b128 v[164:167], v163 offset:50176
	ds_read_b128 v[168:171], v163 offset:51200
	ds_read_b128 v[172:175], v163 offset:52224
	ds_read_b128 v[176:179], v163 offset:53248
	ds_read_b128 v[180:183], v163 offset:54272
	ds_read_b128 v[184:187], v163 offset:55296
	ds_read_b128 v[188:191], v163 offset:56320
	global_load_lds_dwordx4 v[158:159], off
	v_lshl_add_u64 v[158:159], s[74:75], 0, v[150:151]
	s_mov_b32 m0, s94
	s_nop 0
	global_load_lds_dwordx4 v[158:159], off
	s_barrier
; #define G_STAGE(bufoff, gbase, voff) do { _Pragma("unroll") for (int _i = 0; _i < 2; ++_i) \
;         __builtin_amdgcn_global_load_lds((const unsigned*)((const char*)(gbase) + (voff)[_i]), (LAS unsigned*)(lds + (bufoff) + ldsw + _i * 8192), 16, 0, 0); } while (0)
; #define G_BAR __builtin_amdgcn_s_barrier()
; template <class J>
; DI void gemm_phase(LAS unsigned char* lds, const J& job) {
;     ...
;     for (int t = 0; t < nt; t += 2) {
;       const bool last = (t == nt - 2);
;       const char* a1 = cA + G_KT(t + 1);
;       const char* a2 = last ? nA + G_KT(0) : cA + G_KT(t + 2); const char* b2 = last ? nB + G_KT(0) : cB + G_KT(t + 2);
;       const char* a3 = last ? nA + G_KT(1) : cA + G_KT(t + 3); const char* b3 = last ? nB + G_KT(1) : cB + G_KT(t + 3);
;       G_LDB(B0, 0, 0); G_SCHED; G_LDA(At, 0, 0); G_STAGE(G_SA(1, 1), a1 + hstepA, voffA);
;       G_WAIT_L(8); G_BAR; G_WAIT_L(0); G_MMA(0, 0, At, B0); G_BAR; G_SCHED;
;       G_LDB(B1, 0, 1); G_STAGE(G_SB(0, 0), b2, voffB);
;       G_BAR; G_WAIT_L(0); G_MMA(0, 1, At, B1); G_BAR;
;       G_LDA(At, 0, 1); G_STAGE(G_SA(0, 0), a2, voffA);
;       G_BAR; G_WAIT_L(0); G_MMA(1, 0, At, B0); G_BAR; G_SCHED;
;       G_STAGE(G_SB(0, 1), b2 + hstepB, voffB);
;       G_WAIT_V(6); G_BAR; G_MMA(1, 1, At, B1); G_BAR;
;       G_LDB(B0, 1, 0); G_SCHED; G_LDA(At, 1, 0); G_STAGE(G_SA(0, 1), a2 + hstepA, voffA);
;       G_WAIT_L(8); G_BAR; G_WAIT_L(0); G_MMA(0, 0, At, B0); G_BAR; G_SCHED;
;       G_LDB(B1, 1, 1); G_STAGE(G_SB(1, 0), b3, voffB);
;       G_BAR; G_WAIT_L(0); G_MMA(0, 1, At, B1); G_BAR;
;       G_LDA(At, 1, 1); G_STAGE(G_SA(1, 0), a3, voffA);
;       G_BAR; G_WAIT_L(0); G_MMA(1, 0, At, B0); G_BAR; G_SCHED;
;       G_STAGE(G_SB(1, 1), b3 + hstepB, voffB);
;       G_WAIT_V(6); G_BAR; G_MMA(1, 1, At, B1); G_BAR;
;   DI void epi(const Acc& acc, const Unit& u, int wr, int wc, int fr, int fq) const {
;     ...
;     for (int ai = 0; ai < 2; ++ai) {
;       f32x4 res[4][2][2];
; #pragma unroll
;       for (int m = 0; m < 4; ++m) {
;         const int row = u.pm * 256 + ai * HALF + wr * 64 + m * 16 + fr;
;         const float* src = (l == 0) ? xp + (size_t)row * DM : out + (size_t)row * DM;
; #pragma unroll
;         for (int bj = 0; bj < 2; ++bj) { const int col = u.pn * 256 + bj * HALF + wc * 32 + 8 * fq; res[m][bj][0] = *(const f32x4*)(src + col); res[m][bj][1] = *(const f32x4*)(src + col + 4); }
;       }
	s_waitcnt lgkmcnt(0)
	s_setprio 1
	s_waitcnt lgkmcnt(0)
	v_mfma_f32_16x16x32_bf16 v[60:63], v[128:131], v[154:157], v[60:63]
	v_mfma_f32_16x16x32_bf16 v[56:59], v[136:139], v[154:157], v[56:59]
	v_mfma_f32_16x16x32_bf16 v[44:47], v[128:131], v[168:171], v[44:47]
	v_mfma_f32_16x16x32_bf16 v[40:43], v[136:139], v[168:171], v[40:43]
	v_mfma_f32_16x16x32_bf16 v[28:31], v[128:131], v[176:179], v[28:31]
	v_mfma_f32_16x16x32_bf16 v[24:27], v[136:139], v[176:179], v[24:27]
	v_mfma_f32_16x16x32_bf16 v[20:23], v[128:131], v[184:187], v[20:23]
	v_mfma_f32_16x16x32_bf16 v[12:15], v[136:139], v[184:187], v[12:15]
	v_mfma_f32_16x16x32_bf16 v[60:63], v[132:135], v[164:167], v[60:63]
	v_mfma_f32_16x16x32_bf16 v[56:59], v[140:143], v[164:167], v[56:59]
	v_mfma_f32_16x16x32_bf16 v[44:47], v[132:135], v[172:175], v[44:47]
	v_mfma_f32_16x16x32_bf16 v[40:43], v[140:143], v[172:175], v[40:43]
	v_mfma_f32_16x16x32_bf16 v[28:31], v[132:135], v[180:183], v[28:31]
	v_mfma_f32_16x16x32_bf16 v[24:27], v[140:143], v[180:183], v[24:27]
	v_mfma_f32_16x16x32_bf16 v[20:23], v[132:135], v[188:191], v[20:23]
	v_mfma_f32_16x16x32_bf16 v[12:15], v[140:143], v[188:191], v[12:15]
	s_setprio 0
	s_barrier
	s_add_u32 s0, s72, 0x80000
	s_addc_u32 s1, s73, 0
	s_add_i32 s2, s54, s14
	v_lshl_add_u64 v[128:129], s[0:1], 0, v[146:147]
	s_mov_b32 m0, s2
	s_nop 0
	global_load_lds_dwordx4 v[128:129], off
	v_lshl_add_u64 v[128:129], s[0:1], 0, v[152:153]
	s_add_i32 m0, s2, 0x2000
	s_nop 0
	global_load_lds_dwordx4 v[128:129], off
	s_waitcnt vmcnt(6)
	s_barrier
	s_setprio 1
	v_mfma_f32_16x16x32_bf16 v[52:55], v[192:195], v[154:157], v[52:55]
	v_mfma_f32_16x16x32_bf16 v[48:51], v[200:203], v[154:157], v[48:51]
	v_mfma_f32_16x16x32_bf16 v[36:39], v[192:195], v[168:171], v[36:39]
	v_mfma_f32_16x16x32_bf16 v[32:35], v[200:203], v[168:171], v[32:35]
	v_mfma_f32_16x16x32_bf16 v[16:19], v[192:195], v[176:179], v[16:19]
	v_mfma_f32_16x16x32_bf16 v[8:11], v[200:203], v[176:179], v[8:11]
	v_mfma_f32_16x16x32_bf16 v[4:7], v[192:195], v[184:187], v[4:7]
	v_mfma_f32_16x16x32_bf16 v[0:3], v[200:203], v[184:187], v[0:3]
	v_mfma_f32_16x16x32_bf16 v[52:55], v[196:199], v[164:167], v[52:55]
	v_mfma_f32_16x16x32_bf16 v[48:51], v[204:207], v[164:167], v[48:51]
	v_mfma_f32_16x16x32_bf16 v[36:39], v[196:199], v[172:175], v[36:39]
	v_mfma_f32_16x16x32_bf16 v[32:35], v[204:207], v[172:175], v[32:35]
	v_mfma_f32_16x16x32_bf16 v[16:19], v[196:199], v[180:183], v[16:19]
	v_mfma_f32_16x16x32_bf16 v[8:11], v[204:207], v[180:183], v[8:11]
	v_mfma_f32_16x16x32_bf16 v[4:7], v[196:199], v[188:191], v[4:7]
	v_mfma_f32_16x16x32_bf16 v[0:3], v[204:207], v[188:191], v[0:3]
	s_setprio 0
	s_add_i32 s7, s7, 2
	s_addk_i32 s57, 0x100
	s_addk_i32 s44, 0x100
	s_add_i32 s1, s57, 0xffffff80
	s_and_b32 s0, s44, 0xf80
	s_and_b32 s1, s1, 0xf00
	s_add_u32 s2, s70, s1
	s_addc_u32 s72, s71, 0
	s_add_u32 s1, s68, s1
	s_addc_u32 s73, s69, 0
	s_and_b32 s74, s57, 0xf80
	s_add_u32 s80, s70, s74
	s_addc_u32 s75, s71, 0
	s_add_u32 s54, s68, s74
	s_addc_u32 s55, s69, 0
	s_cmp_eq_u32 s7, 28
	s_cselect_b32 s77, vcc_lo, s72
	s_cselect_b32 s76, s47, s2
	s_cselect_b32 s79, s33, s73
	s_cselect_b32 s78, vcc_hi, s1
	s_cselect_b32 s75, s4, s75
	s_cselect_b32 s74, s97, s80
	s_cselect_b32 s73, s6, s55
	s_cselect_b32 s72, s5, s54
	s_cmp_gt_u32 s7, 29
	s_barrier
	s_cbranch_scc0 .LBB0_42
	s_lshl_b32 s0, s66, 8
	v_mov_b32_e32 v128, v161
	v_mov_b32_e32 v129, v160
	s_add_i32 s0, s0, s67
	s_and_b64 vcc, exec, s[18:19]
	v_add_u32_e32 v156, s0, v129
	s_lshl_b32 s0, s46, 8
	s_or_b32 s0, s0, s83
	v_lshl_add_u32 v128, v128, 3, s0
	v_ashrrev_i32_e32 v157, 31, v156
	v_ashrrev_i32_e32 v129, 31, v128
	v_lshlrev_b64 v[212:213], 13, v[156:157]
	v_lshl_add_u64 v[130:131], s[8:9], 0, v[212:213]
	v_lshlrev_b64 v[154:155], 2, v[128:129]
	v_lshl_add_u64 v[128:129], v[130:131], 0, v[154:155]
	global_load_dwordx4 v[164:167], v[128:129], off offset:16
	global_load_dwordx4 v[168:171], v[128:129], off
	global_load_dwordx4 v[172:175], v[128:129], off offset:528
	global_load_dwordx4 v[176:179], v[128:129], off offset:512
	v_add_u32_e32 v128, 16, v156
	v_ashrrev_i32_e32 v129, 31, v128
	v_lshlrev_b64 v[214:215], 13, v[128:129]
	v_lshl_add_u64 v[128:129], s[8:9], 0, v[214:215]
	v_lshl_add_u64 v[128:129], v[128:129], 0, v[154:155]
	global_load_dwordx4 v[180:183], v[128:129], off offset:16
	global_load_dwordx4 v[184:187], v[128:129], off
	global_load_dwordx4 v[188:191], v[128:129], off offset:528
	global_load_dwordx4 v[192:195], v[128:129], off offset:512
	v_add_u32_e32 v128, 32, v156
	v_ashrrev_i32_e32 v129, 31, v128
	v_lshlrev_b64 v[216:217], 13, v[128:129]
	v_lshl_add_u64 v[128:129], s[8:9], 0, v[216:217]
	v_lshl_add_u64 v[128:129], v[128:129], 0, v[154:155]
	global_load_dwordx4 v[196:199], v[128:129], off offset:16
	global_load_dwordx4 v[200:203], v[128:129], off
	global_load_dwordx4 v[204:207], v[128:129], off offset:528
	global_load_dwordx4 v[208:211], v[128:129], off offset:512
	v_add_u32_e32 v128, 48, v156
	v_ashrrev_i32_e32 v129, 31, v128
	v_lshlrev_b64 v[158:159], 13, v[128:129]
	v_lshl_add_u64 v[128:129], s[8:9], 0, v[158:159]
	v_lshl_add_u64 v[136:137], v[128:129], 0, v[154:155]
	global_load_dwordx4 v[132:135], v[136:137], off offset:16
	global_load_dwordx4 v[140:143], v[136:137], off
	global_load_dwordx4 v[128:131], v[136:137], off offset:528
	s_nop 0
	global_load_dwordx4 v[136:139], v[136:137], off offset:512
	v_lshl_add_u64 v[212:213], s[16:17], 0, v[212:213]
	s_mov_b32 s46, s22
	s_mov_b32 s66, s20
	s_mov_b64 s[68:69], s[64:65]
	s_mov_b64 s[70:71], s[62:63]
	s_movk_i32 s54, 0x4000
	s_movk_i32 s55, 0x6000
	v_readlane_b32 s0, v255, 23
	s_cmpk_gt_u32 s0, 0xff
	s_cbranch_scc1 .Lds_out_x
	s_barrier

;   DI const char* aptr(const Unit& u) const { return (const char*)(h + (size_t)u.pm * 256 * DM); }
;   DI const char* bptr(const Unit& u) const { return (const char*)(winT + (size_t)u.pn * 256 * DM); }
;   DI bool next(int i, Unit& u) const { const int L = i * G + c; if (L >= nunits) return false; u.kind = 0; decode_unit(L, 65, 32, u.pm, u.pn); return true; }
;   DI const char* aptr(const Unit& u) const { return (const char*)(y + (size_t)u.pm * 256 * DM + (u.pn >> 3) * 512); }
;   DI const char* bptr(const Unit& u) const { return (const char*)(wbT + (size_t)u.pn * 256 * 512); }
;   DI const char* aptr(const Unit& u) const { return (const char*)(h + (size_t)u.pm * 256 * DM); }
;   DI const char* bptr(const Unit& u) const { return (const char*)(wgT + (size_t)u.pn * 64 * DM); }
;   DI const char* aptr(const Unit& u) const { return (const char*)(mixed + (size_t)u.pm * 256 * DM); }
;   DI const char* bptr(const Unit& u) const { return (const char*)(woutT + (size_t)u.pn * 256 * DM); }
; template <class J>
; DI void gemm_phase(LAS unsigned char* lds, const J& job) {
;     ...
;     const bool has_next = job.next(ui + 1, nxt);
;     const char* nA = has_next ? job.aptr(nxt) : cA; const char* nB = has_next ? job.bptr(nxt) : cB;
;     for (int t = 0; t < nt; t += 2) {
;       const bool last = (t == nt - 2);
;       const char* a1 = cA + G_KT(t + 1);
;       const char* a2 = last ? nA + G_KT(0) : cA + G_KT(t + 2); const char* b2 = last ? nB + G_KT(0) : cB + G_KT(t + 2);
;       const char* a3 = last ? nA + G_KT(1) : cA + G_KT(t + 3); const char* b3 = last ? nB + G_KT(1) : cB + G_KT(t + 3);
;     ...
; #pragma unroll
;     for (int a = 0; a < 2; ++a)
; #pragma unroll
;       for (int b = 0; b < 2; ++b)
; #pragma unroll
;         for (int m = 0; m < 4; ++m)
; #pragma unroll
;           for (int n = 0; n < 2; ++n) acc[a][b][m][n] = (f32x4){0.f, 0.f, 0.f, 0.f};
.LBB0_73:
	s_ashr_i32 s19, s18, 31
	s_lshl_b64 s[6:7], s[18:19], 20
	s_add_u32 s22, s58, s6
	s_addc_u32 s23, s59, s7
	s_ashr_i32 s21, s20, 31
	s_lshl_b64 s[6:7], s[20:21], 18
	s_add_u32 s62, s16, s6
	s_addc_u32 s63, s17, s7
	s_add_u32 s19, s68, 0x80000
	s_addc_u32 s21, s69, 0
	s_and_b64 s[6:7], s[70:71], exec
	s_cselect_b32 s6, s22, s68
	s_cselect_b32 s0, s63, s67
	s_cselect_b32 s1, s62, s66
	s_cselect_b32 s5, s23, s69
	s_add_u32 s45, s6, s65
	s_addc_u32 s46, s5, 0
	s_add_u32 s47, s1, s65
	s_addc_u32 vcc_lo, s0, 0
	s_add_u32 s33, s6, s94
	s_addc_u32 s97, s5, 0
	s_add_u32 vcc_hi, s1, s94
	v_mov_b32_e32 v0, 0
	s_addc_u32 s5, s0, 0
	s_mov_b32 s6, -2
	s_mov_b32 s7, s86
	s_mov_b32 s56, s4
	v_mov_b32_e32 v1, v0
	v_mov_b32_e32 v2, v0
	v_mov_b32_e32 v3, v0
	v_mov_b32_e32 v4, v0
	v_mov_b32_e32 v5, v0
	v_mov_b32_e32 v6, v0
	v_mov_b32_e32 v7, v0
	v_mov_b32_e32 v16, v0
	v_mov_b32_e32 v17, v0
	v_mov_b32_e32 v18, v0
	v_mov_b32_e32 v19, v0
	v_mov_b32_e32 v20, v0
	v_mov_b32_e32 v21, v0
	v_mov_b32_e32 v22, v0
	v_mov_b32_e32 v23, v0
	v_mov_b32_e32 v32, v0
	v_mov_b32_e32 v33, v0
	v_mov_b32_e32 v34, v0
	v_mov_b32_e32 v35, v0
	v_mov_b32_e32 v36, v0
	v_mov_b32_e32 v37, v0
	v_mov_b32_e32 v38, v0
	v_mov_b32_e32 v39, v0
	v_mov_b32_e32 v48, v0
	v_mov_b32_e32 v49, v0
	v_mov_b32_e32 v50, v0
	v_mov_b32_e32 v51, v0
	v_mov_b32_e32 v52, v0
	v_mov_b32_e32 v53, v0
	v_mov_b32_e32 v54, v0
	v_mov_b32_e32 v55, v0
	v_mov_b32_e32 v8, v0
	v_mov_b32_e32 v9, v0
	v_mov_b32_e32 v10, v0
	v_mov_b32_e32 v11, v0
	v_mov_b32_e32 v12, v0
	v_mov_b32_e32 v13, v0
	v_mov_b32_e32 v14, v0
	v_mov_b32_e32 v15, v0
	v_mov_b32_e32 v24, v0
	v_mov_b32_e32 v25, v0
	v_mov_b32_e32 v26, v0
	v_mov_b32_e32 v27, v0
	v_mov_b32_e32 v28, v0
	v_mov_b32_e32 v29, v0
	v_mov_b32_e32 v30, v0
	v_mov_b32_e32 v31, v0
	v_mov_b32_e32 v40, v0
	v_mov_b32_e32 v41, v0
	v_mov_b32_e32 v42, v0
	v_mov_b32_e32 v43, v0
	v_mov_b32_e32 v44, v0
	v_mov_b32_e32 v45, v0
	v_mov_b32_e32 v46, v0
	v_mov_b32_e32 v47, v0
	v_mov_b32_e32 v56, v0
	v_mov_b32_e32 v57, v0
	v_mov_b32_e32 v58, v0
	v_mov_b32_e32 v59, v0
	v_mov_b32_e32 v60, v0
	v_mov_b32_e32 v61, v0
	v_mov_b32_e32 v62, v0
	v_mov_b32_e32 v63, v0
	v_mov_b32_e32 v64, v0
	v_mov_b32_e32 v65, v0
	v_mov_b32_e32 v66, v0
	v_mov_b32_e32 v67, v0
	v_mov_b32_e32 v68, v0
	v_mov_b32_e32 v69, v0
	v_mov_b32_e32 v70, v0
	v_mov_b32_e32 v71, v0
	v_mov_b32_e32 v80, v0
	v_mov_b32_e32 v81, v0
	v_mov_b32_e32 v82, v0
	v_mov_b32_e32 v83, v0
	v_mov_b32_e32 v92, v0
	v_mov_b32_e32 v93, v0
	v_mov_b32_e32 v94, v0
	v_mov_b32_e32 v95, v0
	v_mov_b32_e32 v112, v0
	v_mov_b32_e32 v113, v0
	v_mov_b32_e32 v114, v0
	v_mov_b32_e32 v115, v0
	v_mov_b32_e32 v116, v0
	v_mov_b32_e32 v117, v0
	v_mov_b32_e32 v118, v0
	v_mov_b32_e32 v119, v0
	v_mov_b32_e32 v128, v0
	v_mov_b32_e32 v129, v0
	v_mov_b32_e32 v130, v0
	v_mov_b32_e32 v131, v0
	v_mov_b32_e32 v132, v0
	v_mov_b32_e32 v133, v0
	v_mov_b32_e32 v134, v0
	v_mov_b32_e32 v135, v0
	v_mov_b32_e32 v72, v0
	v_mov_b32_e32 v73, v0
	v_mov_b32_e32 v74, v0
	v_mov_b32_e32 v75, v0
	v_mov_b32_e32 v76, v0
	v_mov_b32_e32 v77, v0
	v_mov_b32_e32 v78, v0
	v_mov_b32_e32 v79, v0
	v_mov_b32_e32 v104, v0
	v_mov_b32_e32 v105, v0
	v_mov_b32_e32 v106, v0
	v_mov_b32_e32 v107, v0
	v_mov_b32_e32 v108, v0
	v_mov_b32_e32 v109, v0
	v_mov_b32_e32 v110, v0
	v_mov_b32_e32 v111, v0
	v_mov_b32_e32 v120, v0
	v_mov_b32_e32 v121, v0
	v_mov_b32_e32 v122, v0
	v_mov_b32_e32 v123, v0
	v_mov_b32_e32 v124, v0
	v_mov_b32_e32 v125, v0
	v_mov_b32_e32 v126, v0
	v_mov_b32_e32 v127, v0
	v_mov_b32_e32 v136, v0
	v_mov_b32_e32 v137, v0
	v_mov_b32_e32 v138, v0
	v_mov_b32_e32 v139, v0
	v_mov_b32_e32 v140, v0
	v_mov_b32_e32 v141, v0
	v_mov_b32_e32 v142, v0
	v_mov_b32_e32 v143, v0
	s_add_i32 s1, s56, 0xffffff80
	s_and_b32 s0, s7, 0xf80
	s_and_b32 s1, s1, 0xf00
	s_add_u32 s57, s68, s1
	s_addc_u32 s70, s69, 0
	s_add_u32 s1, s66, s1
	s_addc_u32 s71, s67, 0
	s_and_b32 s72, s56, 0xf80
	s_add_u32 s80, s68, s72
	s_addc_u32 s73, s69, 0
	s_add_u32 s38, s66, s72
	s_addc_u32 s2, s67, 0
	s_cmp_eq_u32 s6, 28
	s_cselect_b32 s75, s46, s70
	s_cselect_b32 s74, s45, s57
	s_cselect_b32 s77, vcc_lo, s71
	s_cselect_b32 s76, s47, s1
	s_cselect_b32 s73, s97, s73
	s_cselect_b32 s72, s33, s80
	s_cselect_b32 s71, s5, s2
	s_cselect_b32 s70, vcc_hi, s38
.LBB0_74:
	s_add_i32 s2, s84, 0x100
	v_add_u32_e32 v100, s2, v248
	ds_read_b128 v[84:87], v100
	ds_read_b128 v[88:91], v100 offset:1024
	ds_read_b128 v[96:99], v100 offset:2048
	ds_read_b128 v[100:103], v100 offset:3072
	s_add_u32 s0, s19, s0
	s_addc_u32 s1, s21, 0
	v_lshl_add_u64 v[186:187], s[0:1], 0, v[148:149]
	s_add_i32 m0, s14, 0xc000
	ds_read_b128 v[154:157], v249
	ds_read_b128 v[158:161], v249 offset:1024
	ds_read_b128 v[162:165], v249 offset:2048
	ds_read_b128 v[166:169], v249 offset:3072
	ds_read_b128 v[170:173], v249 offset:4096
	ds_read_b128 v[174:177], v249 offset:5120
	ds_read_b128 v[178:181], v249 offset:6144
	ds_read_b128 v[182:185], v249 offset:7168
	global_load_lds_dwordx4 v[186:187], off
	v_lshl_add_u64 v[186:187], s[0:1], 0, v[150:151]
	s_add_i32 m0, s14, 0xe000
	s_nop 0
	global_load_lds_dwordx4 v[186:187], off
	s_waitcnt lgkmcnt(8)
	s_barrier
; #define G_STAGE(bufoff, gbase, voff) do { _Pragma("unroll") for (int _i = 0; _i < 2; ++_i) \
;         __builtin_amdgcn_global_load_lds((const unsigned*)((const char*)(gbase) + (voff)[_i]), (LAS unsigned*)(lds + (bufoff) + ldsw + _i * 8192), 16, 0, 0); } while (0)
; #define G_LDA(dst, b, h) do { _Pragma("unroll") for (int m = 0; m < 4; ++m) _Pragma("unroll") for (int k = 0; k < 2; ++k) dst[m][k] = *(const LAS bf16x8*)(lds + G_SA(b, h) + aoff + m * 2048 + k * 1024); } while (0)
; #define G_LDB(dst, b, h) do { _Pragma("unroll") for (int n = 0; n < 2; ++n) _Pragma("unroll") for (int k = 0; k < 2; ++k) dst[n][k] = *(const LAS bf16x8*)(lds + G_SB(b, h) + boff + n * 2048 + k * 1024); } while (0)
; #define G_MMA(ai, bj, At, Bt) do { __builtin_amdgcn_s_setprio(1); _Pragma("unroll") for (int m = 0; m < 4; ++m) _Pragma("unroll") for (int n = 0; n < 2; ++n) _Pragma("unroll") for (int k = 0; k < 2; ++k) \
;         acc[ai][bj][m][n] = __builtin_amdgcn_mfma_f32_16x16x32_bf16(Bt[n][k], At[m][k], acc[ai][bj][m][n], 0, 0, 0); __builtin_amdgcn_s_setprio(0); } while (0)
; #define G_WAIT_V(n) asm volatile("s_waitcnt vmcnt(" #n ")" ::: "memory")
; #define G_WAIT_L(n) asm volatile("s_waitcnt lgkmcnt(" #n ")" ::: "memory")
; #define G_BAR __builtin_amdgcn_s_barrier()
; #define G_SCHED __builtin_amdgcn_sched_barrier(0)
; template <class J>
; DI void gemm_phase(LAS unsigned char* lds, const J& job) {
;     ...
;       G_WAIT_L(8); G_BAR; G_WAIT_L(0); G_MMA(0, 0, At, B0); G_BAR; G_SCHED;
;       G_LDB(B1, 0, 1); G_STAGE(G_SB(0, 0), b2, voffB);
;       G_BAR; G_WAIT_L(0); G_MMA(0, 1, At, B1); G_BAR;
;       G_LDA(At, 0, 1); G_STAGE(G_SA(0, 0), a2, voffA);
;       G_BAR; G_WAIT_L(0); G_MMA(1, 0, At, B0); G_BAR; G_SCHED;
;       G_STAGE(G_SB(0, 1), b2 + hstepB, voffB);
;       G_WAIT_V(6); G_BAR; G_MMA(1, 1, At, B1); G_BAR;
;       G_LDB(B0, 1, 0); G_SCHED; G_LDA(At, 1, 0); G_STAGE(G_SA(0, 1), a2 + hstepA, voffA);
	s_waitcnt lgkmcnt(0)
	s_setprio 1
	s_waitcnt lgkmcnt(0)
	v_mfma_f32_16x16x32_bf16 v[140:143], v[84:87], v[154:157], v[140:143]
	v_mfma_f32_16x16x32_bf16 v[136:139], v[96:99], v[154:157], v[136:139]
	v_mfma_f32_16x16x32_bf16 v[124:127], v[84:87], v[162:165], v[124:127]
	v_mfma_f32_16x16x32_bf16 v[120:123], v[96:99], v[162:165], v[120:123]
	v_mfma_f32_16x16x32_bf16 v[108:111], v[84:87], v[170:173], v[108:111]
	v_mfma_f32_16x16x32_bf16 v[104:107], v[96:99], v[170:173], v[104:107]
	v_mfma_f32_16x16x32_bf16 v[76:79], v[84:87], v[178:181], v[76:79]
	v_mfma_f32_16x16x32_bf16 v[72:75], v[96:99], v[178:181], v[72:75]
	v_mfma_f32_16x16x32_bf16 v[140:143], v[88:91], v[158:161], v[140:143]
	v_mfma_f32_16x16x32_bf16 v[136:139], v[100:103], v[158:161], v[136:139]
	v_mfma_f32_16x16x32_bf16 v[124:127], v[88:91], v[166:169], v[124:127]
	v_mfma_f32_16x16x32_bf16 v[120:123], v[100:103], v[166:169], v[120:123]
	v_mfma_f32_16x16x32_bf16 v[108:111], v[88:91], v[174:177], v[108:111]
	v_mfma_f32_16x16x32_bf16 v[104:107], v[100:103], v[174:177], v[104:107]
	v_mfma_f32_16x16x32_bf16 v[76:79], v[88:91], v[182:185], v[76:79]
	v_mfma_f32_16x16x32_bf16 v[72:75], v[100:103], v[182:185], v[72:75]
	s_setprio 0
	s_barrier
	s_add_i32 s38, s85, 0x100
	s_add_i32 s0, s2, s78
	v_add_u32_e32 v198, s38, v248
	v_lshl_add_u64 v[202:203], s[76:77], 0, v[146:147]
	s_mov_b32 m0, s0
	ds_read_b128 v[186:189], v198
	ds_read_b128 v[190:193], v198 offset:1024
	ds_read_b128 v[194:197], v198 offset:2048
	ds_read_b128 v[198:201], v198 offset:3072
	global_load_lds_dwordx4 v[202:203], off
	v_lshl_add_u64 v[202:203], s[76:77], 0, v[152:153]
	s_add_i32 m0, s0, 0x2000
	s_nop 0
	global_load_lds_dwordx4 v[202:203], off
	s_barrier
	s_waitcnt lgkmcnt(0)
	s_setprio 1
	s_waitcnt lgkmcnt(0)
	v_mfma_f32_16x16x32_bf16 v[132:135], v[186:189], v[154:157], v[132:135]
	v_mfma_f32_16x16x32_bf16 v[128:131], v[194:197], v[154:157], v[128:131]
	v_mfma_f32_16x16x32_bf16 v[116:119], v[186:189], v[162:165], v[116:119]
	v_mfma_f32_16x16x32_bf16 v[112:115], v[194:197], v[162:165], v[112:115]
	v_mfma_f32_16x16x32_bf16 v[92:95], v[186:189], v[170:173], v[92:95]
	v_mfma_f32_16x16x32_bf16 v[80:83], v[194:197], v[170:173], v[80:83]
	v_mfma_f32_16x16x32_bf16 v[68:71], v[186:189], v[178:181], v[68:71]
	v_mfma_f32_16x16x32_bf16 v[64:67], v[194:197], v[178:181], v[64:67]
	v_mfma_f32_16x16x32_bf16 v[132:135], v[190:193], v[158:161], v[132:135]
	v_mfma_f32_16x16x32_bf16 v[128:131], v[198:201], v[158:161], v[128:131]
	v_mfma_f32_16x16x32_bf16 v[116:119], v[190:193], v[166:169], v[116:119]
	v_mfma_f32_16x16x32_bf16 v[112:115], v[198:201], v[166:169], v[112:115]
	v_mfma_f32_16x16x32_bf16 v[92:95], v[190:193], v[174:177], v[92:95]
	v_mfma_f32_16x16x32_bf16 v[80:83], v[198:201], v[174:177], v[80:83]
	v_mfma_f32_16x16x32_bf16 v[68:71], v[190:193], v[182:185], v[68:71]
	v_mfma_f32_16x16x32_bf16 v[64:67], v[198:201], v[182:185], v[64:67]
	s_setprio 0
	s_mov_b32 m0, s14
	v_lshl_add_u64 v[202:203], s[74:75], 0, v[148:149]
	s_barrier
	ds_read_b128 v[154:157], v249 offset:16384
	ds_read_b128 v[158:161], v249 offset:17408
	ds_read_b128 v[162:165], v249 offset:18432
	ds_read_b128 v[166:169], v249 offset:19456
	ds_read_b128 v[170:173], v249 offset:20480
	ds_read_b128 v[174:177], v249 offset:21504
	ds_read_b128 v[178:181], v249 offset:22528
	ds_read_b128 v[182:185], v249 offset:23552
	global_load_lds_dwordx4 v[202:203], off
	v_lshl_add_u64 v[202:203], s[74:75], 0, v[150:151]
	s_mov_b32 m0, s15
	s_nop 0
	global_load_lds_dwordx4 v[202:203], off
	s_barrier
	s_waitcnt lgkmcnt(0)
	s_setprio 1
	s_waitcnt lgkmcnt(0)
	v_mfma_f32_16x16x32_bf16 v[60:63], v[84:87], v[154:157], v[60:63]
	v_mfma_f32_16x16x32_bf16 v[56:59], v[96:99], v[154:157], v[56:59]
	v_mfma_f32_16x16x32_bf16 v[44:47], v[84:87], v[162:165], v[44:47]
	v_mfma_f32_16x16x32_bf16 v[40:43], v[96:99], v[162:165], v[40:43]
	v_mfma_f32_16x16x32_bf16 v[28:31], v[84:87], v[170:173], v[28:31]
	v_mfma_f32_16x16x32_bf16 v[24:27], v[96:99], v[170:173], v[24:27]
	v_mfma_f32_16x16x32_bf16 v[12:15], v[84:87], v[178:181], v[12:15]
	v_mfma_f32_16x16x32_bf16 v[8:11], v[96:99], v[178:181], v[8:11]
	v_mfma_f32_16x16x32_bf16 v[60:63], v[88:91], v[158:161], v[60:63]
	v_mfma_f32_16x16x32_bf16 v[56:59], v[100:103], v[158:161], v[56:59]
	v_mfma_f32_16x16x32_bf16 v[44:47], v[88:91], v[166:169], v[44:47]
	v_mfma_f32_16x16x32_bf16 v[40:43], v[100:103], v[166:169], v[40:43]
	v_mfma_f32_16x16x32_bf16 v[28:31], v[88:91], v[174:177], v[28:31]
	v_mfma_f32_16x16x32_bf16 v[24:27], v[100:103], v[174:177], v[24:27]
	v_mfma_f32_16x16x32_bf16 v[12:15], v[88:91], v[182:185], v[12:15]
	v_mfma_f32_16x16x32_bf16 v[8:11], v[100:103], v[182:185], v[8:11]
	s_setprio 0
	s_barrier
	s_add_u32 s0, s76, 0x1000000
	s_addc_u32 s1, s77, 0
	s_add_i32 s2, s38, s78
	v_lshl_add_u64 v[84:85], s[0:1], 0, v[146:147]
	s_mov_b32 m0, s2
	s_nop 0
	global_load_lds_dwordx4 v[84:85], off
	v_lshl_add_u64 v[84:85], s[0:1], 0, v[152:153]
	s_add_i32 m0, s2, 0x2000
	s_nop 0
	global_load_lds_dwordx4 v[84:85], off
	s_waitcnt vmcnt(6)
	s_barrier
	s_setprio 1
	v_mfma_f32_16x16x32_bf16 v[52:55], v[186:189], v[154:157], v[52:55]
	v_mfma_f32_16x16x32_bf16 v[48:51], v[194:197], v[154:157], v[48:51]
	v_mfma_f32_16x16x32_bf16 v[36:39], v[186:189], v[162:165], v[36:39]
	v_mfma_f32_16x16x32_bf16 v[32:35], v[194:197], v[162:165], v[32:35]
	v_mfma_f32_16x16x32_bf16 v[20:23], v[186:189], v[170:173], v[20:23]
	v_mfma_f32_16x16x32_bf16 v[16:19], v[194:197], v[170:173], v[16:19]
	v_mfma_f32_16x16x32_bf16 v[4:7], v[186:189], v[178:181], v[4:7]
	v_mfma_f32_16x16x32_bf16 v[0:3], v[194:197], v[178:181], v[0:3]
	v_mfma_f32_16x16x32_bf16 v[52:55], v[190:193], v[158:161], v[52:55]
	v_mfma_f32_16x16x32_bf16 v[48:51], v[198:201], v[158:161], v[48:51]
	v_mfma_f32_16x16x32_bf16 v[36:39], v[190:193], v[166:169], v[36:39]
	v_mfma_f32_16x16x32_bf16 v[32:35], v[198:201], v[166:169], v[32:35]
	v_mfma_f32_16x16x32_bf16 v[20:23], v[190:193], v[174:177], v[20:23]
	v_mfma_f32_16x16x32_bf16 v[16:19], v[198:201], v[174:177], v[16:19]
	v_mfma_f32_16x16x32_bf16 v[4:7], v[190:193], v[182:185], v[4:7]
	v_mfma_f32_16x16x32_bf16 v[0:3], v[198:201], v[182:185], v[0:3]
	s_setprio 0
	s_add_i32 s2, s88, 0x100
	v_add_u32_e32 v100, s2, v248
	s_barrier
; #define G_STAGE(bufoff, gbase, voff) do { _Pragma("unroll") for (int _i = 0; _i < 2; ++_i) \
;         __builtin_amdgcn_global_load_lds((const unsigned*)((const char*)(gbase) + (voff)[_i]), (LAS unsigned*)(lds + (bufoff) + ldsw + _i * 8192), 16, 0, 0); } while (0)
; #define G_LDA(dst, b, h) do { _Pragma("unroll") for (int m = 0; m < 4; ++m) _Pragma("unroll") for (int k = 0; k < 2; ++k) dst[m][k] = *(const LAS bf16x8*)(lds + G_SA(b, h) + aoff + m * 2048 + k * 1024); } while (0)
; #define G_LDB(dst, b, h) do { _Pragma("unroll") for (int n = 0; n < 2; ++n) _Pragma("unroll") for (int k = 0; k < 2; ++k) dst[n][k] = *(const LAS bf16x8*)(lds + G_SB(b, h) + boff + n * 2048 + k * 1024); } while (0)
; #define G_MMA(ai, bj, At, Bt) do { __builtin_amdgcn_s_setprio(1); _Pragma("unroll") for (int m = 0; m < 4; ++m) _Pragma("unroll") for (int n = 0; n < 2; ++n) _Pragma("unroll") for (int k = 0; k < 2; ++k) \
;         acc[ai][bj][m][n] = __builtin_amdgcn_mfma_f32_16x16x32_bf16(Bt[n][k], At[m][k], acc[ai][bj][m][n], 0, 0, 0); __builtin_amdgcn_s_setprio(0); } while (0)
; #define G_WAIT_L(n) asm volatile("s_waitcnt lgkmcnt(" #n ")" ::: "memory")
; #define G_BAR __builtin_amdgcn_s_barrier()
; #define G_SCHED __builtin_amdgcn_sched_barrier(0)
; template <class J>
; DI void gemm_phase(LAS unsigned char* lds, const J& job) {
;     ...
;       G_LDB(B0, 1, 0); G_SCHED; G_LDA(At, 1, 0); G_STAGE(G_SA(0, 1), a2 + hstepA, voffA);
;       G_WAIT_L(8); G_BAR; G_WAIT_L(0); G_MMA(0, 0, At, B0); G_BAR; G_SCHED;
;       G_LDB(B1, 1, 1); G_STAGE(G_SB(1, 0), b3, voffB);
;       G_BAR; G_WAIT_L(0); G_MMA(0, 1, At, B1); G_BAR;
;       G_LDA(At, 1, 1); G_STAGE(G_SA(1, 0), a3, voffA);
;       G_BAR; G_WAIT_L(0); G_MMA(1, 0, At, B0); G_BAR; G_SCHED;
	ds_read_b128 v[84:87], v100
	ds_read_b128 v[88:91], v100 offset:1024
	ds_read_b128 v[96:99], v100 offset:2048
	ds_read_b128 v[100:103], v100 offset:3072
	s_add_u32 s0, s74, 0x80000
	s_addc_u32 s1, s75, 0
	s_mov_b32 m0, s83
	v_lshl_add_u64 v[186:187], s[0:1], 0, v[148:149]
	ds_read_b128 v[154:157], v249 offset:32768
	ds_read_b128 v[158:161], v249 offset:33792
	ds_read_b128 v[162:165], v249 offset:34816
	ds_read_b128 v[166:169], v249 offset:35840
	ds_read_b128 v[170:173], v249 offset:36864
	ds_read_b128 v[174:177], v249 offset:37888
	ds_read_b128 v[178:181], v249 offset:38912
	ds_read_b128 v[182:185], v249 offset:39936
	global_load_lds_dwordx4 v[186:187], off
	v_lshl_add_u64 v[186:187], s[0:1], 0, v[150:151]
	s_mov_b32 m0, s36
	s_nop 0
	global_load_lds_dwordx4 v[186:187], off
	s_waitcnt lgkmcnt(8)
	s_barrier
	s_waitcnt lgkmcnt(0)
	s_setprio 1
	s_waitcnt lgkmcnt(0)
	v_mfma_f32_16x16x32_bf16 v[140:143], v[84:87], v[154:157], v[140:143]
	v_mfma_f32_16x16x32_bf16 v[136:139], v[96:99], v[154:157], v[136:139]
	v_mfma_f32_16x16x32_bf16 v[124:127], v[84:87], v[162:165], v[124:127]
	v_mfma_f32_16x16x32_bf16 v[120:123], v[96:99], v[162:165], v[120:123]
	v_mfma_f32_16x16x32_bf16 v[108:111], v[84:87], v[170:173], v[108:111]
	v_mfma_f32_16x16x32_bf16 v[104:107], v[96:99], v[170:173], v[104:107]
	v_mfma_f32_16x16x32_bf16 v[76:79], v[84:87], v[178:181], v[76:79]
	v_mfma_f32_16x16x32_bf16 v[72:75], v[96:99], v[178:181], v[72:75]
	v_mfma_f32_16x16x32_bf16 v[140:143], v[88:91], v[158:161], v[140:143]
	v_mfma_f32_16x16x32_bf16 v[136:139], v[100:103], v[158:161], v[136:139]
	v_mfma_f32_16x16x32_bf16 v[124:127], v[88:91], v[166:169], v[124:127]
	v_mfma_f32_16x16x32_bf16 v[120:123], v[100:103], v[166:169], v[120:123]
	v_mfma_f32_16x16x32_bf16 v[108:111], v[88:91], v[174:177], v[108:111]
	v_mfma_f32_16x16x32_bf16 v[104:107], v[100:103], v[174:177], v[104:107]
	v_mfma_f32_16x16x32_bf16 v[76:79], v[88:91], v[182:185], v[76:79]
	v_mfma_f32_16x16x32_bf16 v[72:75], v[100:103], v[182:185], v[72:75]
	s_setprio 0
	s_barrier
	s_add_i32 s38, s89, 0x100
	s_add_i32 s0, s2, s78
	v_add_u32_e32 v198, s38, v248
	v_lshl_add_u64 v[202:203], s[70:71], 0, v[146:147]
	s_mov_b32 m0, s0
	ds_read_b128 v[186:189], v198
	ds_read_b128 v[190:193], v198 offset:1024
	ds_read_b128 v[194:197], v198 offset:2048
	ds_read_b128 v[198:201], v198 offset:3072
	global_load_lds_dwordx4 v[202:203], off
	v_lshl_add_u64 v[202:203], s[70:71], 0, v[152:153]
	s_add_i32 m0, s0, 0x2000
	s_nop 0
	global_load_lds_dwordx4 v[202:203], off
	s_barrier
	s_waitcnt lgkmcnt(0)
	s_setprio 1
	s_waitcnt lgkmcnt(0)
	v_mfma_f32_16x16x32_bf16 v[132:135], v[186:189], v[154:157], v[132:135]
	v_mfma_f32_16x16x32_bf16 v[128:131], v[194:197], v[154:157], v[128:131]
	v_mfma_f32_16x16x32_bf16 v[116:119], v[186:189], v[162:165], v[116:119]
	v_mfma_f32_16x16x32_bf16 v[112:115], v[194:197], v[162:165], v[112:115]
	v_mfma_f32_16x16x32_bf16 v[92:95], v[186:189], v[170:173], v[92:95]
	v_mfma_f32_16x16x32_bf16 v[80:83], v[194:197], v[170:173], v[80:83]
	v_mfma_f32_16x16x32_bf16 v[68:71], v[186:189], v[178:181], v[68:71]
	v_mfma_f32_16x16x32_bf16 v[64:67], v[194:197], v[178:181], v[64:67]
	v_mfma_f32_16x16x32_bf16 v[132:135], v[190:193], v[158:161], v[132:135]
	v_mfma_f32_16x16x32_bf16 v[128:131], v[198:201], v[158:161], v[128:131]
	v_mfma_f32_16x16x32_bf16 v[116:119], v[190:193], v[166:169], v[116:119]
	v_mfma_f32_16x16x32_bf16 v[112:115], v[198:201], v[166:169], v[112:115]
	v_mfma_f32_16x16x32_bf16 v[92:95], v[190:193], v[174:177], v[92:95]
	v_mfma_f32_16x16x32_bf16 v[80:83], v[198:201], v[174:177], v[80:83]
	v_mfma_f32_16x16x32_bf16 v[68:71], v[190:193], v[182:185], v[68:71]
	v_mfma_f32_16x16x32_bf16 v[64:67], v[198:201], v[182:185], v[64:67]
	s_setprio 0
	s_mov_b32 m0, s24
	v_lshl_add_u64 v[202:203], s[72:73], 0, v[148:149]
	s_barrier
	ds_read_b128 v[154:157], v249 offset:49152
	ds_read_b128 v[158:161], v249 offset:50176
	ds_read_b128 v[162:165], v249 offset:51200
	ds_read_b128 v[166:169], v249 offset:52224
	ds_read_b128 v[170:173], v249 offset:53248
	ds_read_b128 v[174:177], v249 offset:54272
	ds_read_b128 v[178:181], v249 offset:55296
	ds_read_b128 v[182:185], v249 offset:56320
	global_load_lds_dwordx4 v[202:203], off
	v_lshl_add_u64 v[202:203], s[72:73], 0, v[150:151]
	s_mov_b32 m0, s25
	s_nop 0
	global_load_lds_dwordx4 v[202:203], off
	s_barrier
	s_waitcnt lgkmcnt(0)
	s_setprio 1
	s_waitcnt lgkmcnt(0)
	v_mfma_f32_16x16x32_bf16 v[60:63], v[84:87], v[154:157], v[60:63]
	v_mfma_f32_16x16x32_bf16 v[56:59], v[96:99], v[154:157], v[56:59]
	v_mfma_f32_16x16x32_bf16 v[44:47], v[84:87], v[162:165], v[44:47]
	v_mfma_f32_16x16x32_bf16 v[40:43], v[96:99], v[162:165], v[40:43]
	v_mfma_f32_16x16x32_bf16 v[28:31], v[84:87], v[170:173], v[28:31]
	v_mfma_f32_16x16x32_bf16 v[24:27], v[96:99], v[170:173], v[24:27]
	v_mfma_f32_16x16x32_bf16 v[12:15], v[84:87], v[178:181], v[12:15]
	v_mfma_f32_16x16x32_bf16 v[8:11], v[96:99], v[178:181], v[8:11]
	v_mfma_f32_16x16x32_bf16 v[60:63], v[88:91], v[158:161], v[60:63]
	v_mfma_f32_16x16x32_bf16 v[56:59], v[100:103], v[158:161], v[56:59]
	v_mfma_f32_16x16x32_bf16 v[44:47], v[88:91], v[166:169], v[44:47]
	v_mfma_f32_16x16x32_bf16 v[40:43], v[100:103], v[166:169], v[40:43]
	v_mfma_f32_16x16x32_bf16 v[28:31], v[88:91], v[174:177], v[28:31]
	v_mfma_f32_16x16x32_bf16 v[24:27], v[100:103], v[174:177], v[24:27]
	v_mfma_f32_16x16x32_bf16 v[12:15], v[88:91], v[182:185], v[12:15]
	v_mfma_f32_16x16x32_bf16 v[8:11], v[100:103], v[182:185], v[8:11]
	s_setprio 0
	s_barrier
; #define G_STAGE(bufoff, gbase, voff) do { _Pragma("unroll") for (int _i = 0; _i < 2; ++_i) \
;         __builtin_amdgcn_global_load_lds((const unsigned*)((const char*)(gbase) + (voff)[_i]), (LAS unsigned*)(lds + (bufoff) + ldsw + _i * 8192), 16, 0, 0); } while (0)
; #define G_MMA(ai, bj, At, Bt) do { __builtin_amdgcn_s_setprio(1); _Pragma("unroll") for (int m = 0; m < 4; ++m) _Pragma("unroll") for (int n = 0; n < 2; ++n) _Pragma("unroll") for (int k = 0; k < 2; ++k) \
;         acc[ai][bj][m][n] = __builtin_amdgcn_mfma_f32_16x16x32_bf16(Bt[n][k], At[m][k], acc[ai][bj][m][n], 0, 0, 0); __builtin_amdgcn_s_setprio(0); } while (0)
; #define G_WAIT_V(n) asm volatile("s_waitcnt vmcnt(" #n ")" ::: "memory")
; #define G_BAR __builtin_amdgcn_s_barrier()
; template <class J>
; DI void gemm_phase(LAS unsigned char* lds, const J& job) {
;     ...
;     for (int t = 0; t < nt; t += 2) {
;       const bool last = (t == nt - 2);
;       const char* a1 = cA + G_KT(t + 1);
;       const char* a2 = last ? nA + G_KT(0) : cA + G_KT(t + 2); const char* b2 = last ? nB + G_KT(0) : cB + G_KT(t + 2);
;       const char* a3 = last ? nA + G_KT(1) : cA + G_KT(t + 3); const char* b3 = last ? nB + G_KT(1) : cB + G_KT(t + 3);
;     ...
;       G_STAGE(G_SB(1, 1), b3 + hstepB, voffB);
;       G_WAIT_V(6); G_BAR; G_MMA(1, 1, At, B1); G_BAR;
	s_add_u32 s0, s70, 0x1000000
	s_addc_u32 s1, s71, 0
	s_add_i32 s2, s38, s78
	v_lshl_add_u64 v[84:85], s[0:1], 0, v[146:147]
	s_mov_b32 m0, s2
	s_nop 0
	global_load_lds_dwordx4 v[84:85], off
	v_lshl_add_u64 v[84:85], s[0:1], 0, v[152:153]
	s_add_i32 m0, s2, 0x2000
	s_nop 0
	global_load_lds_dwordx4 v[84:85], off
	s_waitcnt vmcnt(6)
	s_barrier
	s_setprio 1
	v_mfma_f32_16x16x32_bf16 v[52:55], v[186:189], v[154:157], v[52:55]
	v_mfma_f32_16x16x32_bf16 v[48:51], v[194:197], v[154:157], v[48:51]
	v_mfma_f32_16x16x32_bf16 v[36:39], v[186:189], v[162:165], v[36:39]
	v_mfma_f32_16x16x32_bf16 v[32:35], v[194:197], v[162:165], v[32:35]
	v_mfma_f32_16x16x32_bf16 v[20:23], v[186:189], v[170:173], v[20:23]
	v_mfma_f32_16x16x32_bf16 v[16:19], v[194:197], v[170:173], v[16:19]
	v_mfma_f32_16x16x32_bf16 v[4:7], v[186:189], v[178:181], v[4:7]
	v_mfma_f32_16x16x32_bf16 v[0:3], v[194:197], v[178:181], v[0:3]
	v_mfma_f32_16x16x32_bf16 v[52:55], v[190:193], v[158:161], v[52:55]
	v_mfma_f32_16x16x32_bf16 v[48:51], v[198:201], v[158:161], v[48:51]
	v_mfma_f32_16x16x32_bf16 v[36:39], v[190:193], v[166:169], v[36:39]
	v_mfma_f32_16x16x32_bf16 v[32:35], v[198:201], v[166:169], v[32:35]
	v_mfma_f32_16x16x32_bf16 v[20:23], v[190:193], v[174:177], v[20:23]
	v_mfma_f32_16x16x32_bf16 v[16:19], v[198:201], v[174:177], v[16:19]
	v_mfma_f32_16x16x32_bf16 v[4:7], v[190:193], v[182:185], v[4:7]
	v_mfma_f32_16x16x32_bf16 v[0:3], v[198:201], v[182:185], v[0:3]
	s_setprio 0
	s_add_i32 s6, s6, 2
	s_addk_i32 s56, 0x100
	s_addk_i32 s7, 0x100
	s_add_i32 s1, s56, 0xffffff80
	s_and_b32 s0, s7, 0xf80
	s_and_b32 s1, s1, 0xf00
	s_add_u32 s57, s68, s1
	s_addc_u32 s70, s69, 0
	s_add_u32 s1, s66, s1
	s_addc_u32 s71, s67, 0
	s_and_b32 s72, s56, 0xf80
	s_add_u32 s80, s68, s72
	s_addc_u32 s73, s69, 0
	s_add_u32 s38, s66, s72
	s_addc_u32 s2, s67, 0
	s_cmp_eq_u32 s6, 28
	s_cselect_b32 s75, s46, s70
	s_cselect_b32 s74, s45, s57
	s_cselect_b32 s77, vcc_lo, s71
	s_cselect_b32 s76, s47, s1
	s_cselect_b32 s73, s97, s73
	s_cselect_b32 s72, s33, s80
	s_cselect_b32 s71, s5, s2
	s_cselect_b32 s70, vcc_hi, s38
	s_cmp_gt_u32 s6, 29
	s_barrier
	s_cbranch_scc0 .LBB0_74
;   DI void epi(const Acc& acc, const Unit& u, int wr, int wc, int fr, int fq) const {
;     const int cc = u.pn * 64 + 16 * wc + 4 * fq;
;     u32x2 zz[2][4][4];
; #pragma unroll
;     for (int ai = 0; ai < 2; ++ai)
; #pragma unroll
;       for (int m = 0; m < 4; ++m) {
;         const u16* zr = Z + (size_t)(u.pm * 256 + ai * HALF + wr * 64 + m * 16 + fr) * NGATE + cc;
; #pragma unroll
;         for (int br = 0; br < 4; ++br) zz[ai][m][br] = *(const u32x2*)(zr + br * 2048);
;       }
;     f32x4 bg[4];
; #pragma unroll
;     for (int br = 0; br < 4; ++br) bg[br] = *(const f32x4*)(bgate + br * 2048 + cc);
;     asm volatile("" ::: "memory");
	v_mov_b32_e32 v84, v247
	v_mov_b32_e32 v85, v246
	s_lshl_b32 s0, s44, 6
	s_or_b32 s0, s0, s96
	v_lshl_add_u32 v84, v84, 2, s0
	s_lshl_b32 s0, s64, 8
	s_add_i32 s0, s0, s37
	v_add_u32_e32 v224, s0, v85
	v_ashrrev_i32_e32 v85, 31, v84
	v_lshlrev_b64 v[154:155], 1, v[84:85]
	v_ashrrev_i32_e32 v225, 31, v224
	v_lshl_add_u64 v[86:87], s[26:27], 0, v[154:155]
	v_lshlrev_b64 v[88:89], 14, v[224:225]
	v_lshl_add_u64 v[88:89], v[86:87], 0, v[88:89]
	v_add_co_u32_e32 v90, vcc, s82, v88
	v_add_u32_e32 v212, 16, v224
	s_nop 0
	v_addc_co_u32_e32 v91, vcc, 0, v89, vcc
	v_ashrrev_i32_e32 v213, 31, v212
	v_add_co_u32_e32 v96, vcc, s92, v88
	v_lshlrev_b64 v[98:99], 14, v[212:213]
	s_nop 0
	v_addc_co_u32_e32 v97, vcc, 0, v89, vcc
	v_lshl_add_u64 v[98:99], v[86:87], 0, v[98:99]
	v_add_co_u32_e32 v100, vcc, s82, v98
	v_add_u32_e32 v202, 32, v224
	s_nop 0
	v_addc_co_u32_e32 v101, vcc, 0, v99, vcc
	global_load_dwordx2 v[230:231], v[90:91], off offset:-4096
	global_load_dwordx2 v[226:227], v[90:91], off
	global_load_dwordx2 v[220:221], v[100:101], off offset:-4096
	global_load_dwordx2 v[214:215], v[100:101], off
	v_add_co_u32_e32 v90, vcc, s92, v98
	v_ashrrev_i32_e32 v203, 31, v202
	s_nop 0
	v_addc_co_u32_e32 v91, vcc, 0, v99, vcc
	global_load_dwordx2 v[232:233], v[88:89], off
	global_load_dwordx2 v[228:229], v[96:97], off
	global_load_dwordx2 v[222:223], v[98:99], off
	global_load_dwordx2 v[216:217], v[90:91], off
	v_lshlrev_b64 v[88:89], 14, v[202:203]
	v_lshl_add_u64 v[88:89], v[86:87], 0, v[88:89]
	v_add_co_u32_e32 v90, vcc, s82, v88
	v_add_u32_e32 v190, 48, v224
	s_nop 0
	v_addc_co_u32_e32 v91, vcc, 0, v89, vcc
	v_ashrrev_i32_e32 v191, 31, v190
	v_add_co_u32_e32 v96, vcc, s92, v88
	v_lshlrev_b64 v[98:99], 14, v[190:191]
	s_nop 0
	v_addc_co_u32_e32 v97, vcc, 0, v89, vcc
	v_lshl_add_u64 v[98:99], v[86:87], 0, v[98:99]
	v_add_co_u32_e32 v100, vcc, s82, v98
	v_add_u32_e32 v184, 0x80, v224
	s_nop 0
	v_addc_co_u32_e32 v101, vcc, 0, v99, vcc
	global_load_dwordx2 v[210:211], v[90:91], off offset:-4096
	global_load_dwordx2 v[206:207], v[90:91], off
	global_load_dwordx2 v[200:201], v[100:101], off offset:-4096
	global_load_dwordx2 v[192:193], v[100:101], off
	v_add_co_u32_e32 v90, vcc, s92, v98
	v_lshl_add_u64 v[84:85], v[84:85], 2, s[12:13]
	v_ashrrev_i32_e32 v185, 31, v184
	v_addc_co_u32_e32 v91, vcc, 0, v99, vcc
	global_load_dwordx4 v[100:103], v[84:85], off
	global_load_dwordx2 v[218:219], v[88:89], off
	global_load_dwordx2 v[208:209], v[96:97], off
	global_load_dwordx2 v[204:205], v[98:99], off
	global_load_dwordx2 v[198:199], v[90:91], off
	v_lshlrev_b64 v[88:89], 14, v[184:185]
	v_lshl_add_u64 v[88:89], v[86:87], 0, v[88:89]
	v_add_co_u32_e32 v90, vcc, s82, v88
	v_add_u32_e32 v174, 0x90, v224
	s_nop 0
	v_addc_co_u32_e32 v91, vcc, 0, v89, vcc
	v_add_co_u32_e32 v156, vcc, s92, v88
	v_ashrrev_i32_e32 v175, 31, v174
	s_nop 0
	v_addc_co_u32_e32 v157, vcc, 0, v89, vcc
	v_add_co_u32_e32 v96, vcc, s82, v84
	v_lshlrev_b64 v[158:159], 14, v[174:175]
	s_nop 0
	v_addc_co_u32_e32 v97, vcc, 0, v85, vcc
	global_load_dwordx4 v[96:99], v[96:97], off
	v_lshl_add_u64 v[158:159], v[86:87], 0, v[158:159]
	v_add_co_u32_e32 v160, vcc, s82, v158
	v_add_u32_e32 v164, 0xa0, v224
	s_nop 0
	v_addc_co_u32_e32 v161, vcc, 0, v159, vcc
	global_load_dwordx2 v[194:195], v[90:91], off offset:-4096
	global_load_dwordx2 v[186:187], v[90:91], off
	global_load_dwordx2 v[180:181], v[160:161], off offset:-4096
	global_load_dwordx2 v[176:177], v[160:161], off
	v_add_co_u32_e32 v90, vcc, s92, v158
	v_ashrrev_i32_e32 v165, 31, v164
	s_nop 0
	v_addc_co_u32_e32 v91, vcc, 0, v159, vcc
	global_load_dwordx2 v[196:197], v[88:89], off
	global_load_dwordx2 v[188:189], v[156:157], off
	global_load_dwordx2 v[182:183], v[158:159], off
	global_load_dwordx2 v[178:179], v[90:91], off
	v_lshlrev_b64 v[88:89], 14, v[164:165]
	v_lshl_add_u64 v[162:163], v[86:87], 0, v[88:89]
	v_add_co_u32_e32 v158, vcc, s82, v162
	v_add_u32_e32 v156, 0xb0, v224
	s_nop 0
	v_addc_co_u32_e32 v159, vcc, 0, v163, vcc
	v_add_co_u32_e32 v168, vcc, s92, v162
	v_ashrrev_i32_e32 v157, 31, v156
	s_nop 0
	v_addc_co_u32_e32 v169, vcc, 0, v163, vcc
	v_add_co_u32_e32 v88, vcc, s54, v84
	v_lshlrev_b64 v[160:161], 14, v[156:157]
	s_nop 0
	v_addc_co_u32_e32 v89, vcc, 0, v85, vcc
	global_load_dwordx4 v[88:91], v[88:89], off
	v_lshl_add_u64 v[250:251], v[86:87], 0, v[160:161]
	v_add_co_u32_e32 v86, vcc, s82, v250
	s_mov_b32 s44, s20
	s_nop 0
	v_addc_co_u32_e32 v87, vcc, 0, v251, vcc
	v_add_co_u32_e32 v84, vcc, s55, v84
	global_load_dwordx2 v[170:171], v[158:159], off offset:-4096
	global_load_dwordx2 v[166:167], v[158:159], off
	global_load_dwordx2 v[160:161], v[86:87], off offset:-4096
	s_nop 0
	global_load_dwordx2 v[158:159], v[86:87], off
	v_addc_co_u32_e32 v85, vcc, 0, v85, vcc
	global_load_dwordx4 v[84:87], v[84:85], off
	v_add_co_u32_e32 v252, vcc, s92, v250
	s_mov_b32 s64, s18
	s_nop 0
	v_addc_co_u32_e32 v253, vcc, 0, v251, vcc
	s_and_b64 vcc, exec, s[8:9]
	s_mov_b64 s[66:67], s[62:63]
	s_mov_b64 s[68:69], s[22:23]
	v_readlane_b32 s0, v255, 23
	s_cmpk_gt_u32 s0, 0xff
	s_cbranch_scc1 .Lds_gate_x
	s_barrier

;   DI const char* aptr(const Unit& u) const { return (const char*)(h + (size_t)u.pm * 256 * DM); }
;   DI const char* bptr(const Unit& u) const { return (const char*)(winT + (size_t)u.pn * 256 * DM); }
;   DI bool next(int i, Unit& u) const { const int L = i * G + c; if (L >= nunits) return false; u.kind = 0; decode_unit(L, 65, 32, u.pm, u.pn); return true; }
;   DI const char* aptr(const Unit& u) const { return (const char*)(h + (size_t)u.pm * 256 * DM); }
;   DI const char* bptr(const Unit& u) const { return (const char*)(wgT + (size_t)u.pn * 64 * DM); }
;   DI const char* aptr(const Unit& u) const { return (const char*)(mixed + (size_t)u.pm * 256 * DM); }
;   DI const char* bptr(const Unit& u) const { return (const char*)(woutT + (size_t)u.pn * 256 * DM); }
; template <class J>
; DI void gemm_phase(LAS unsigned char* lds, const J& job) {
;     ...
;     const bool has_next = job.next(ui + 1, nxt);
;     const char* nA = has_next ? job.aptr(nxt) : cA; const char* nB = has_next ? job.bptr(nxt) : cB;
;     for (int t = 0; t < nt; t += 2) {
;       const bool last = (t == nt - 2);
;       const char* a1 = cA + G_KT(t + 1);
;       const char* a2 = last ? nA + G_KT(0) : cA + G_KT(t + 2); const char* b2 = last ? nB + G_KT(0) : cB + G_KT(t + 2);
;       const char* a3 = last ? nA + G_KT(1) : cA + G_KT(t + 3); const char* b3 = last ? nB + G_KT(1) : cB + G_KT(t + 3);
;   DI const char* aptr(const Unit& u) const { return (const char*)(y + (size_t)u.pm * 256 * DM + (u.pn >> 3) * 512); }
;   DI const char* bptr(const Unit& u) const { return (const char*)(wbT + (size_t)u.pn * 256 * 512); }
.LBB0_103:
	s_lshl_b32 s0, s8, 6
	s_ashr_i32 s17, s16, 31
	s_and_b32 s18, s0, 0xfffffe00
	s_lshl_b64 s[6:7], s[16:17], 20
	s_ashr_i32 s19, s18, 31
	s_add_u32 s0, s10, s6
	s_addc_u32 s1, s11, s7
	s_lshl_b64 s[6:7], s[18:19], 1
	s_add_u32 s18, s0, s6
	s_addc_u32 s19, s1, s7
	s_ashr_i32 s9, s8, 31
	s_lshl_b64 s[6:7], s[8:9], 18
	s_add_u32 s20, s14, s6
	s_addc_u32 s21, s15, s7
	s_add_u32 s9, s64, 0x80000
	s_addc_u32 s17, s65, 0
	s_and_b64 s[6:7], s[66:67], exec
	s_cselect_b32 s6, s18, s64
	s_cselect_b32 s0, s21, s63
	s_cselect_b32 s1, s20, s62
	s_cselect_b32 s5, s19, s65
	s_add_u32 s47, s6, s23
	s_addc_u32 s83, s5, 0
	s_add_u32 s86, s1, s23
	s_addc_u32 s87, s0, 0
	s_add_u32 s33, s6, s74
	s_addc_u32 s94, s5, 0
	s_add_u32 s96, s1, s74
	v_mov_b32_e32 v0, 0
	s_addc_u32 s5, s0, 0
	s_mov_b32 s6, -2
	s_mov_b32 s7, s78
	s_mov_b32 s56, s77
	v_mov_b32_e32 v1, v0
	v_mov_b32_e32 v2, v0
	v_mov_b32_e32 v3, v0
	v_mov_b32_e32 v4, v0
	v_mov_b32_e32 v5, v0
	v_mov_b32_e32 v6, v0
	v_mov_b32_e32 v7, v0
	v_mov_b32_e32 v8, v0
	v_mov_b32_e32 v9, v0
	v_mov_b32_e32 v10, v0
	v_mov_b32_e32 v11, v0
	v_mov_b32_e32 v16, v0
	v_mov_b32_e32 v17, v0
	v_mov_b32_e32 v18, v0
	v_mov_b32_e32 v19, v0
	v_mov_b32_e32 v24, v0
	v_mov_b32_e32 v25, v0
	v_mov_b32_e32 v26, v0
	v_mov_b32_e32 v27, v0
	v_mov_b32_e32 v32, v0
	v_mov_b32_e32 v33, v0
	v_mov_b32_e32 v34, v0
	v_mov_b32_e32 v35, v0
	v_mov_b32_e32 v40, v0
	v_mov_b32_e32 v41, v0
	v_mov_b32_e32 v42, v0
	v_mov_b32_e32 v43, v0
	v_mov_b32_e32 v48, v0
	v_mov_b32_e32 v49, v0
	v_mov_b32_e32 v50, v0
	v_mov_b32_e32 v51, v0
	v_mov_b32_e32 v12, v0
	v_mov_b32_e32 v13, v0
	v_mov_b32_e32 v14, v0
	v_mov_b32_e32 v15, v0
	v_mov_b32_e32 v20, v0
	v_mov_b32_e32 v21, v0
	v_mov_b32_e32 v22, v0
	v_mov_b32_e32 v23, v0
	v_mov_b32_e32 v28, v0
	v_mov_b32_e32 v29, v0
	v_mov_b32_e32 v30, v0
	v_mov_b32_e32 v31, v0
	v_mov_b32_e32 v36, v0
	v_mov_b32_e32 v37, v0
	v_mov_b32_e32 v38, v0
	v_mov_b32_e32 v39, v0
	v_mov_b32_e32 v44, v0
	v_mov_b32_e32 v45, v0
	v_mov_b32_e32 v46, v0
	v_mov_b32_e32 v47, v0
	v_mov_b32_e32 v52, v0
	v_mov_b32_e32 v53, v0
	v_mov_b32_e32 v54, v0
	v_mov_b32_e32 v55, v0
	v_mov_b32_e32 v56, v0
	v_mov_b32_e32 v57, v0
	v_mov_b32_e32 v58, v0
	v_mov_b32_e32 v59, v0
	v_mov_b32_e32 v60, v0
	v_mov_b32_e32 v61, v0
	v_mov_b32_e32 v62, v0
	v_mov_b32_e32 v63, v0
	v_mov_b32_e32 v64, v0
	v_mov_b32_e32 v65, v0
	v_mov_b32_e32 v66, v0
	v_mov_b32_e32 v67, v0
	v_mov_b32_e32 v68, v0
	v_mov_b32_e32 v69, v0
	v_mov_b32_e32 v70, v0
	v_mov_b32_e32 v71, v0
	v_mov_b32_e32 v72, v0
	v_mov_b32_e32 v73, v0
	v_mov_b32_e32 v74, v0
	v_mov_b32_e32 v75, v0
	v_mov_b32_e32 v80, v0
	v_mov_b32_e32 v81, v0
	v_mov_b32_e32 v82, v0
	v_mov_b32_e32 v83, v0
	v_mov_b32_e32 v88, v0
	v_mov_b32_e32 v89, v0
	v_mov_b32_e32 v90, v0
	v_mov_b32_e32 v91, v0
	v_mov_b32_e32 v96, v0
	v_mov_b32_e32 v97, v0
	v_mov_b32_e32 v98, v0
	v_mov_b32_e32 v99, v0
	v_mov_b32_e32 v104, v0
	v_mov_b32_e32 v105, v0
	v_mov_b32_e32 v106, v0
	v_mov_b32_e32 v107, v0
	v_mov_b32_e32 v112, v0
	v_mov_b32_e32 v113, v0
	v_mov_b32_e32 v114, v0
	v_mov_b32_e32 v115, v0
	v_mov_b32_e32 v76, v0
	v_mov_b32_e32 v77, v0
	v_mov_b32_e32 v78, v0
	v_mov_b32_e32 v79, v0
	v_mov_b32_e32 v84, v0
	v_mov_b32_e32 v85, v0
	v_mov_b32_e32 v86, v0
	v_mov_b32_e32 v87, v0
	v_mov_b32_e32 v92, v0
	v_mov_b32_e32 v93, v0
	v_mov_b32_e32 v94, v0
	v_mov_b32_e32 v95, v0
	v_mov_b32_e32 v100, v0
	v_mov_b32_e32 v101, v0
	v_mov_b32_e32 v102, v0
	v_mov_b32_e32 v103, v0
	v_mov_b32_e32 v108, v0
	v_mov_b32_e32 v109, v0
	v_mov_b32_e32 v110, v0
	v_mov_b32_e32 v111, v0
	v_mov_b32_e32 v116, v0
	v_mov_b32_e32 v117, v0
	v_mov_b32_e32 v118, v0
	v_mov_b32_e32 v119, v0
	v_mov_b32_e32 v120, v0
	v_mov_b32_e32 v121, v0
	v_mov_b32_e32 v122, v0
	v_mov_b32_e32 v123, v0
	v_mov_b32_e32 v124, v0
	v_mov_b32_e32 v125, v0
	v_mov_b32_e32 v126, v0
	v_mov_b32_e32 v127, v0
	s_add_i32 s1, s56, 0xffffff80
	s_and_b32 s0, s7, 0x380
	s_and_b32 s1, s1, 0x380
	s_add_u32 s57, s64, s1
	s_addc_u32 s66, s65, 0
	s_add_u32 s1, s62, s1
	s_addc_u32 s67, s63, 0
	s_and_b32 s68, s56, 0x380
	s_add_u32 s80, s64, s68
	s_addc_u32 s69, s65, 0
	s_add_u32 s97, s62, s68
	s_addc_u32 vcc_lo, s63, 0
	s_cmp_eq_u32 s6, 4
	s_cselect_b32 s71, s83, s66
	s_cselect_b32 s70, s47, s57
	s_cselect_b32 s73, s87, s67
	s_cselect_b32 s72, s86, s1
	s_cselect_b32 s69, s94, s69
	s_cselect_b32 s68, s33, s80
	s_cselect_b32 s67, s5, vcc_lo
	s_cselect_b32 s66, s96, s97
; #define G_STAGE(bufoff, gbase, voff) do { _Pragma("unroll") for (int _i = 0; _i < 2; ++_i) \
;         __builtin_amdgcn_global_load_lds((const unsigned*)((const char*)(gbase) + (voff)[_i]), (LAS unsigned*)(lds + (bufoff) + ldsw + _i * 8192), 16, 0, 0); } while (0)
; #define G_LDA(dst, b, h) do { _Pragma("unroll") for (int m = 0; m < 4; ++m) _Pragma("unroll") for (int k = 0; k < 2; ++k) dst[m][k] = *(const LAS bf16x8*)(lds + G_SA(b, h) + aoff + m * 2048 + k * 1024); } while (0)
; #define G_LDB(dst, b, h) do { _Pragma("unroll") for (int n = 0; n < 2; ++n) _Pragma("unroll") for (int k = 0; k < 2; ++k) dst[n][k] = *(const LAS bf16x8*)(lds + G_SB(b, h) + boff + n * 2048 + k * 1024); } while (0)
; #define G_MMA(ai, bj, At, Bt) do { __builtin_amdgcn_s_setprio(1); _Pragma("unroll") for (int m = 0; m < 4; ++m) _Pragma("unroll") for (int n = 0; n < 2; ++n) _Pragma("unroll") for (int k = 0; k < 2; ++k) \
;         acc[ai][bj][m][n] = __builtin_amdgcn_mfma_f32_16x16x32_bf16(Bt[n][k], At[m][k], acc[ai][bj][m][n], 0, 0, 0); __builtin_amdgcn_s_setprio(0); } while (0)
; #define G_WAIT_L(n) asm volatile("s_waitcnt lgkmcnt(" #n ")" ::: "memory")
; #define G_BAR __builtin_amdgcn_s_barrier()
; #define G_SCHED __builtin_amdgcn_sched_barrier(0)
; template <class J>
; DI void gemm_phase(LAS unsigned char* lds, const J& job) {
;     ...
;       G_LDB(B0, 0, 0); G_SCHED; G_LDA(At, 0, 0); G_STAGE(G_SA(1, 1), a1 + hstepA, voffA);
;       G_WAIT_L(8); G_BAR; G_WAIT_L(0); G_MMA(0, 0, At, B0); G_BAR; G_SCHED;
;       G_LDB(B1, 0, 1); G_STAGE(G_SB(0, 0), b2, voffB);
;       G_BAR; G_WAIT_L(0); G_MMA(0, 1, At, B1); G_BAR;
;       G_LDA(At, 0, 1); G_STAGE(G_SA(0, 0), a2, voffA);
;       G_BAR; G_WAIT_L(0); G_MMA(1, 0, At, B0); G_BAR; G_SCHED;
.LBB0_104:
	s_add_i32 s1, s84, 0x100
	v_add_u32_e32 v134, s1, v138
	ds_read_b128 v[140:143], v134
	ds_read_b128 v[148:151], v134 offset:1024
	ds_read_b128 v[152:155], v134 offset:2048
	ds_read_b128 v[156:159], v134 offset:3072
	s_add_u32 vcc_lo, s9, s0
	s_addc_u32 vcc_hi, s17, 0
	v_lshl_add_u64 v[134:135], vcc, 0, v[132:133]
	s_add_i32 m0, s25, 0xc000
	ds_read_b128 v[160:163], v139
	ds_read_b128 v[164:167], v139 offset:1024
	ds_read_b128 v[168:171], v139 offset:2048
	ds_read_b128 v[172:175], v139 offset:3072
	ds_read_b128 v[176:179], v139 offset:4096
	ds_read_b128 v[180:183], v139 offset:5120
	ds_read_b128 v[184:187], v139 offset:6144
	ds_read_b128 v[188:191], v139 offset:7168
	global_load_lds_dwordx4 v[134:135], off
	v_lshl_add_u64 v[134:135], vcc, 0, v[130:131]
	s_add_i32 m0, s25, 0xe000
	s_nop 0
	global_load_lds_dwordx4 v[134:135], off
	s_waitcnt lgkmcnt(8)
	s_barrier
	s_waitcnt lgkmcnt(0)
	s_setprio 1
	s_waitcnt lgkmcnt(0)
	v_mfma_f32_16x16x32_bf16 v[124:127], v[140:143], v[160:163], v[124:127]
	v_mfma_f32_16x16x32_bf16 v[120:123], v[152:155], v[160:163], v[120:123]
	v_mfma_f32_16x16x32_bf16 v[116:119], v[140:143], v[168:171], v[116:119]
	v_mfma_f32_16x16x32_bf16 v[108:111], v[152:155], v[168:171], v[108:111]
	v_mfma_f32_16x16x32_bf16 v[100:103], v[140:143], v[176:179], v[100:103]
	v_mfma_f32_16x16x32_bf16 v[92:95], v[152:155], v[176:179], v[92:95]
	v_mfma_f32_16x16x32_bf16 v[84:87], v[140:143], v[184:187], v[84:87]
	v_mfma_f32_16x16x32_bf16 v[76:79], v[152:155], v[184:187], v[76:79]
	v_mfma_f32_16x16x32_bf16 v[124:127], v[148:151], v[164:167], v[124:127]
	v_mfma_f32_16x16x32_bf16 v[120:123], v[156:159], v[164:167], v[120:123]
	v_mfma_f32_16x16x32_bf16 v[116:119], v[148:151], v[172:175], v[116:119]
	v_mfma_f32_16x16x32_bf16 v[108:111], v[156:159], v[172:175], v[108:111]
	v_mfma_f32_16x16x32_bf16 v[100:103], v[148:151], v[180:183], v[100:103]
	v_mfma_f32_16x16x32_bf16 v[92:95], v[156:159], v[180:183], v[92:95]
	v_mfma_f32_16x16x32_bf16 v[84:87], v[148:151], v[188:191], v[84:87]
	v_mfma_f32_16x16x32_bf16 v[76:79], v[156:159], v[188:191], v[76:79]
	s_setprio 0
	s_barrier
	s_add_i32 s0, s85, 0x100
	v_add_u32_e32 v134, s0, v138
	s_add_i32 s1, s1, s24
	ds_read_b128 v[192:195], v134
	ds_read_b128 v[196:199], v134 offset:1024
	ds_read_b128 v[200:203], v134 offset:2048
	ds_read_b128 v[204:207], v134 offset:3072
	v_lshl_add_u64 v[134:135], s[72:73], 0, v[146:147]
	s_mov_b32 m0, s1
	s_nop 0
	global_load_lds_dwordx4 v[134:135], off
	v_lshl_add_u64 v[134:135], s[72:73], 0, v[128:129]
	s_add_i32 m0, s1, 0x2000
	s_nop 0
	global_load_lds_dwordx4 v[134:135], off
	s_barrier
	s_waitcnt lgkmcnt(0)
	s_setprio 1
	s_waitcnt lgkmcnt(0)
	v_mfma_f32_16x16x32_bf16 v[112:115], v[192:195], v[160:163], v[112:115]
	v_mfma_f32_16x16x32_bf16 v[104:107], v[200:203], v[160:163], v[104:107]
	v_mfma_f32_16x16x32_bf16 v[96:99], v[192:195], v[168:171], v[96:99]
	v_mfma_f32_16x16x32_bf16 v[88:91], v[200:203], v[168:171], v[88:91]
	v_mfma_f32_16x16x32_bf16 v[80:83], v[192:195], v[176:179], v[80:83]
	v_mfma_f32_16x16x32_bf16 v[72:75], v[200:203], v[176:179], v[72:75]
	v_mfma_f32_16x16x32_bf16 v[68:71], v[192:195], v[184:187], v[68:71]
	v_mfma_f32_16x16x32_bf16 v[64:67], v[200:203], v[184:187], v[64:67]
	v_mfma_f32_16x16x32_bf16 v[112:115], v[196:199], v[164:167], v[112:115]
	v_mfma_f32_16x16x32_bf16 v[104:107], v[204:207], v[164:167], v[104:107]
	v_mfma_f32_16x16x32_bf16 v[96:99], v[196:199], v[172:175], v[96:99]
	v_mfma_f32_16x16x32_bf16 v[88:91], v[204:207], v[172:175], v[88:91]
	v_mfma_f32_16x16x32_bf16 v[80:83], v[196:199], v[180:183], v[80:83]
	v_mfma_f32_16x16x32_bf16 v[72:75], v[204:207], v[180:183], v[72:75]
	v_mfma_f32_16x16x32_bf16 v[68:71], v[196:199], v[188:191], v[68:71]
	v_mfma_f32_16x16x32_bf16 v[64:67], v[204:207], v[188:191], v[64:67]
	s_setprio 0
	s_mov_b32 m0, s25
	v_lshl_add_u64 v[134:135], s[70:71], 0, v[132:133]
	s_barrier
	ds_read_b128 v[160:163], v139 offset:16384
	ds_read_b128 v[164:167], v139 offset:17408
	ds_read_b128 v[168:171], v139 offset:18432
	ds_read_b128 v[172:175], v139 offset:19456
	ds_read_b128 v[176:179], v139 offset:20480
	ds_read_b128 v[180:183], v139 offset:21504
	ds_read_b128 v[184:187], v139 offset:22528
	ds_read_b128 v[188:191], v139 offset:23552
	global_load_lds_dwordx4 v[134:135], off
	v_lshl_add_u64 v[134:135], s[70:71], 0, v[130:131]
	s_mov_b32 m0, s36
	s_nop 0
	global_load_lds_dwordx4 v[134:135], off
	s_barrier
	s_waitcnt lgkmcnt(0)
	s_setprio 1
	s_waitcnt lgkmcnt(0)
	v_mfma_f32_16x16x32_bf16 v[60:63], v[140:143], v[160:163], v[60:63]
	v_mfma_f32_16x16x32_bf16 v[56:59], v[152:155], v[160:163], v[56:59]
	v_mfma_f32_16x16x32_bf16 v[52:55], v[140:143], v[168:171], v[52:55]
	v_mfma_f32_16x16x32_bf16 v[44:47], v[152:155], v[168:171], v[44:47]
	v_mfma_f32_16x16x32_bf16 v[36:39], v[140:143], v[176:179], v[36:39]
	v_mfma_f32_16x16x32_bf16 v[28:31], v[152:155], v[176:179], v[28:31]
	v_mfma_f32_16x16x32_bf16 v[20:23], v[140:143], v[184:187], v[20:23]
	v_mfma_f32_16x16x32_bf16 v[12:15], v[152:155], v[184:187], v[12:15]
	v_mfma_f32_16x16x32_bf16 v[60:63], v[148:151], v[164:167], v[60:63]
	v_mfma_f32_16x16x32_bf16 v[56:59], v[156:159], v[164:167], v[56:59]
	v_mfma_f32_16x16x32_bf16 v[52:55], v[148:151], v[172:175], v[52:55]
	v_mfma_f32_16x16x32_bf16 v[44:47], v[156:159], v[172:175], v[44:47]
	v_mfma_f32_16x16x32_bf16 v[36:39], v[148:151], v[180:183], v[36:39]
	v_mfma_f32_16x16x32_bf16 v[28:31], v[156:159], v[180:183], v[28:31]
	v_mfma_f32_16x16x32_bf16 v[20:23], v[148:151], v[188:191], v[20:23]
	v_mfma_f32_16x16x32_bf16 v[12:15], v[156:159], v[188:191], v[12:15]
	s_setprio 0
	s_barrier
; #define G_STAGE(bufoff, gbase, voff) do { _Pragma("unroll") for (int _i = 0; _i < 2; ++_i) \
;         __builtin_amdgcn_global_load_lds((const unsigned*)((const char*)(gbase) + (voff)[_i]), (LAS unsigned*)(lds + (bufoff) + ldsw + _i * 8192), 16, 0, 0); } while (0)
; #define G_LDA(dst, b, h) do { _Pragma("unroll") for (int m = 0; m < 4; ++m) _Pragma("unroll") for (int k = 0; k < 2; ++k) dst[m][k] = *(const LAS bf16x8*)(lds + G_SA(b, h) + aoff + m * 2048 + k * 1024); } while (0)
; #define G_LDB(dst, b, h) do { _Pragma("unroll") for (int n = 0; n < 2; ++n) _Pragma("unroll") for (int k = 0; k < 2; ++k) dst[n][k] = *(const LAS bf16x8*)(lds + G_SB(b, h) + boff + n * 2048 + k * 1024); } while (0)
; #define G_MMA(ai, bj, At, Bt) do { __builtin_amdgcn_s_setprio(1); _Pragma("unroll") for (int m = 0; m < 4; ++m) _Pragma("unroll") for (int n = 0; n < 2; ++n) _Pragma("unroll") for (int k = 0; k < 2; ++k) \
;         acc[ai][bj][m][n] = __builtin_amdgcn_mfma_f32_16x16x32_bf16(Bt[n][k], At[m][k], acc[ai][bj][m][n], 0, 0, 0); __builtin_amdgcn_s_setprio(0); } while (0)
; #define G_WAIT_V(n) asm volatile("s_waitcnt vmcnt(" #n ")" ::: "memory")
; #define G_WAIT_L(n) asm volatile("s_waitcnt lgkmcnt(" #n ")" ::: "memory")
; #define G_BAR __builtin_amdgcn_s_barrier()
; #define G_SCHED __builtin_amdgcn_sched_barrier(0)
; template <class J>
; DI void gemm_phase(LAS unsigned char* lds, const J& job) {
;     ...
;       G_STAGE(G_SB(0, 1), b2 + hstepB, voffB);
;       G_WAIT_V(6); G_BAR; G_MMA(1, 1, At, B1); G_BAR;
;       G_LDB(B0, 1, 0); G_SCHED; G_LDA(At, 1, 0); G_STAGE(G_SA(0, 1), a2 + hstepA, voffA);
;       G_WAIT_L(8); G_BAR; G_WAIT_L(0); G_MMA(0, 0, At, B0); G_BAR; G_SCHED;
;       G_LDB(B1, 1, 1); G_STAGE(G_SB(1, 0), b3, voffB);
;       G_BAR; G_WAIT_L(0); G_MMA(0, 1, At, B1); G_BAR;
;       G_LDA(At, 1, 1); G_STAGE(G_SA(1, 0), a3, voffA);
	s_add_u32 s72, s72, 0x20000
	s_addc_u32 s73, s73, 0
	s_add_i32 s0, s0, s24
	v_lshl_add_u64 v[134:135], s[72:73], 0, v[146:147]
	s_mov_b32 m0, s0
	s_nop 0
	global_load_lds_dwordx4 v[134:135], off
	v_lshl_add_u64 v[134:135], s[72:73], 0, v[128:129]
	s_add_i32 m0, s0, 0x2000
	s_nop 0
	global_load_lds_dwordx4 v[134:135], off
	s_waitcnt vmcnt(6)
	s_barrier
	s_setprio 1
	v_mfma_f32_16x16x32_bf16 v[48:51], v[192:195], v[160:163], v[48:51]
	v_mfma_f32_16x16x32_bf16 v[40:43], v[200:203], v[160:163], v[40:43]
	v_mfma_f32_16x16x32_bf16 v[32:35], v[192:195], v[168:171], v[32:35]
	v_mfma_f32_16x16x32_bf16 v[24:27], v[200:203], v[168:171], v[24:27]
	v_mfma_f32_16x16x32_bf16 v[16:19], v[192:195], v[176:179], v[16:19]
	v_mfma_f32_16x16x32_bf16 v[8:11], v[200:203], v[176:179], v[8:11]
	v_mfma_f32_16x16x32_bf16 v[4:7], v[192:195], v[184:187], v[4:7]
	v_mfma_f32_16x16x32_bf16 v[0:3], v[200:203], v[184:187], v[0:3]
	v_mfma_f32_16x16x32_bf16 v[48:51], v[196:199], v[164:167], v[48:51]
	v_mfma_f32_16x16x32_bf16 v[40:43], v[204:207], v[164:167], v[40:43]
	v_mfma_f32_16x16x32_bf16 v[32:35], v[196:199], v[172:175], v[32:35]
	v_mfma_f32_16x16x32_bf16 v[24:27], v[204:207], v[172:175], v[24:27]
	v_mfma_f32_16x16x32_bf16 v[16:19], v[196:199], v[180:183], v[16:19]
	v_mfma_f32_16x16x32_bf16 v[8:11], v[204:207], v[180:183], v[8:11]
	v_mfma_f32_16x16x32_bf16 v[4:7], v[196:199], v[188:191], v[4:7]
	v_mfma_f32_16x16x32_bf16 v[0:3], v[204:207], v[188:191], v[0:3]
	s_setprio 0
	s_add_i32 s0, s88, 0x100
	v_add_u32_e32 v134, s0, v138
	s_barrier
	ds_read_b128 v[140:143], v134
	ds_read_b128 v[148:151], v134 offset:1024
	ds_read_b128 v[152:155], v134 offset:2048
	ds_read_b128 v[156:159], v134 offset:3072
	s_add_u32 s70, s70, 0x80000
	s_addc_u32 s71, s71, 0
	s_mov_b32 m0, s37
	v_lshl_add_u64 v[134:135], s[70:71], 0, v[132:133]
	ds_read_b128 v[160:163], v139 offset:32768
	ds_read_b128 v[164:167], v139 offset:33792
	ds_read_b128 v[168:171], v139 offset:34816
	ds_read_b128 v[172:175], v139 offset:35840
	ds_read_b128 v[176:179], v139 offset:36864
	ds_read_b128 v[180:183], v139 offset:37888
	ds_read_b128 v[184:187], v139 offset:38912
	ds_read_b128 v[188:191], v139 offset:39936
	global_load_lds_dwordx4 v[134:135], off
	v_lshl_add_u64 v[134:135], s[70:71], 0, v[130:131]
	s_mov_b32 m0, s38
	s_nop 0
	global_load_lds_dwordx4 v[134:135], off
	s_waitcnt lgkmcnt(8)
	s_barrier
	s_waitcnt lgkmcnt(0)
	s_setprio 1
	s_waitcnt lgkmcnt(0)
	v_mfma_f32_16x16x32_bf16 v[124:127], v[140:143], v[160:163], v[124:127]
	v_mfma_f32_16x16x32_bf16 v[120:123], v[152:155], v[160:163], v[120:123]
	v_mfma_f32_16x16x32_bf16 v[116:119], v[140:143], v[168:171], v[116:119]
	v_mfma_f32_16x16x32_bf16 v[108:111], v[152:155], v[168:171], v[108:111]
	v_mfma_f32_16x16x32_bf16 v[100:103], v[140:143], v[176:179], v[100:103]
	v_mfma_f32_16x16x32_bf16 v[92:95], v[152:155], v[176:179], v[92:95]
	v_mfma_f32_16x16x32_bf16 v[84:87], v[140:143], v[184:187], v[84:87]
	v_mfma_f32_16x16x32_bf16 v[76:79], v[152:155], v[184:187], v[76:79]
	v_mfma_f32_16x16x32_bf16 v[124:127], v[148:151], v[164:167], v[124:127]
	v_mfma_f32_16x16x32_bf16 v[120:123], v[156:159], v[164:167], v[120:123]
	v_mfma_f32_16x16x32_bf16 v[116:119], v[148:151], v[172:175], v[116:119]
	v_mfma_f32_16x16x32_bf16 v[108:111], v[156:159], v[172:175], v[108:111]
	v_mfma_f32_16x16x32_bf16 v[100:103], v[148:151], v[180:183], v[100:103]
	v_mfma_f32_16x16x32_bf16 v[92:95], v[156:159], v[180:183], v[92:95]
	v_mfma_f32_16x16x32_bf16 v[84:87], v[148:151], v[188:191], v[84:87]
	v_mfma_f32_16x16x32_bf16 v[76:79], v[156:159], v[188:191], v[76:79]
	s_setprio 0
	s_barrier
	s_add_i32 s1, s89, 0x100
	v_add_u32_e32 v134, s1, v138
	s_add_i32 s0, s0, s24
	ds_read_b128 v[192:195], v134
	ds_read_b128 v[196:199], v134 offset:1024
	ds_read_b128 v[200:203], v134 offset:2048
	ds_read_b128 v[204:207], v134 offset:3072
	v_lshl_add_u64 v[134:135], s[66:67], 0, v[146:147]
	s_mov_b32 m0, s0
	s_nop 0
	global_load_lds_dwordx4 v[134:135], off
	v_lshl_add_u64 v[134:135], s[66:67], 0, v[128:129]
	s_add_i32 m0, s0, 0x2000
	s_nop 0
	global_load_lds_dwordx4 v[134:135], off
	s_barrier
	s_waitcnt lgkmcnt(0)
	s_setprio 1
	s_waitcnt lgkmcnt(0)
	v_mfma_f32_16x16x32_bf16 v[112:115], v[192:195], v[160:163], v[112:115]
	v_mfma_f32_16x16x32_bf16 v[104:107], v[200:203], v[160:163], v[104:107]
	v_mfma_f32_16x16x32_bf16 v[96:99], v[192:195], v[168:171], v[96:99]
	v_mfma_f32_16x16x32_bf16 v[88:91], v[200:203], v[168:171], v[88:91]
	v_mfma_f32_16x16x32_bf16 v[80:83], v[192:195], v[176:179], v[80:83]
	v_mfma_f32_16x16x32_bf16 v[72:75], v[200:203], v[176:179], v[72:75]
	v_mfma_f32_16x16x32_bf16 v[68:71], v[192:195], v[184:187], v[68:71]
	v_mfma_f32_16x16x32_bf16 v[64:67], v[200:203], v[184:187], v[64:67]
	v_mfma_f32_16x16x32_bf16 v[112:115], v[196:199], v[164:167], v[112:115]
	v_mfma_f32_16x16x32_bf16 v[104:107], v[204:207], v[164:167], v[104:107]
	v_mfma_f32_16x16x32_bf16 v[96:99], v[196:199], v[172:175], v[96:99]
	v_mfma_f32_16x16x32_bf16 v[88:91], v[204:207], v[172:175], v[88:91]
	v_mfma_f32_16x16x32_bf16 v[80:83], v[196:199], v[180:183], v[80:83]
	v_mfma_f32_16x16x32_bf16 v[72:75], v[204:207], v[180:183], v[72:75]
	v_mfma_f32_16x16x32_bf16 v[68:71], v[196:199], v[188:191], v[68:71]
	v_mfma_f32_16x16x32_bf16 v[64:67], v[204:207], v[188:191], v[64:67]
	s_setprio 0
	s_mov_b32 m0, s75
	v_lshl_add_u64 v[134:135], s[68:69], 0, v[132:133]
	s_barrier
	ds_read_b128 v[160:163], v139 offset:49152
	ds_read_b128 v[164:167], v139 offset:50176
	ds_read_b128 v[168:171], v139 offset:51200
	ds_read_b128 v[172:175], v139 offset:52224
	ds_read_b128 v[176:179], v139 offset:53248
	ds_read_b128 v[180:183], v139 offset:54272
	ds_read_b128 v[184:187], v139 offset:55296
	ds_read_b128 v[188:191], v139 offset:56320
	global_load_lds_dwordx4 v[134:135], off
	v_lshl_add_u64 v[134:135], s[68:69], 0, v[130:131]
	s_mov_b32 m0, s76
	s_nop 0
	global_load_lds_dwordx4 v[134:135], off
	s_barrier
; #define G_STAGE(bufoff, gbase, voff) do { _Pragma("unroll") for (int _i = 0; _i < 2; ++_i) \
;         __builtin_amdgcn_global_load_lds((const unsigned*)((const char*)(gbase) + (voff)[_i]), (LAS unsigned*)(lds + (bufoff) + ldsw + _i * 8192), 16, 0, 0); } while (0)
; #define G_MMA(ai, bj, At, Bt) do { __builtin_amdgcn_s_setprio(1); _Pragma("unroll") for (int m = 0; m < 4; ++m) _Pragma("unroll") for (int n = 0; n < 2; ++n) _Pragma("unroll") for (int k = 0; k < 2; ++k) \
;         acc[ai][bj][m][n] = __builtin_amdgcn_mfma_f32_16x16x32_bf16(Bt[n][k], At[m][k], acc[ai][bj][m][n], 0, 0, 0); __builtin_amdgcn_s_setprio(0); } while (0)
; #define G_WAIT_V(n) asm volatile("s_waitcnt vmcnt(" #n ")" ::: "memory")
; #define G_WAIT_L(n) asm volatile("s_waitcnt lgkmcnt(" #n ")" ::: "memory")
; #define G_BAR __builtin_amdgcn_s_barrier()
; #define G_SCHED __builtin_amdgcn_sched_barrier(0)
; template <class J>
; DI void gemm_phase(LAS unsigned char* lds, const J& job) {
;     ...
;     for (int t = 0; t < nt; t += 2) {
;       const bool last = (t == nt - 2);
;       const char* a1 = cA + G_KT(t + 1);
;       const char* a2 = last ? nA + G_KT(0) : cA + G_KT(t + 2); const char* b2 = last ? nB + G_KT(0) : cB + G_KT(t + 2);
;       const char* a3 = last ? nA + G_KT(1) : cA + G_KT(t + 3); const char* b3 = last ? nB + G_KT(1) : cB + G_KT(t + 3);
;     ...
;       G_BAR; G_WAIT_L(0); G_MMA(1, 0, At, B0); G_BAR; G_SCHED;
;       G_STAGE(G_SB(1, 1), b3 + hstepB, voffB);
;       G_WAIT_V(6); G_BAR; G_MMA(1, 1, At, B1); G_BAR;
	s_waitcnt lgkmcnt(0)
	s_setprio 1
	s_waitcnt lgkmcnt(0)
	v_mfma_f32_16x16x32_bf16 v[60:63], v[140:143], v[160:163], v[60:63]
	v_mfma_f32_16x16x32_bf16 v[56:59], v[152:155], v[160:163], v[56:59]
	v_mfma_f32_16x16x32_bf16 v[52:55], v[140:143], v[168:171], v[52:55]
	v_mfma_f32_16x16x32_bf16 v[44:47], v[152:155], v[168:171], v[44:47]
	v_mfma_f32_16x16x32_bf16 v[36:39], v[140:143], v[176:179], v[36:39]
	v_mfma_f32_16x16x32_bf16 v[28:31], v[152:155], v[176:179], v[28:31]
	v_mfma_f32_16x16x32_bf16 v[20:23], v[140:143], v[184:187], v[20:23]
	v_mfma_f32_16x16x32_bf16 v[12:15], v[152:155], v[184:187], v[12:15]
	v_mfma_f32_16x16x32_bf16 v[60:63], v[148:151], v[164:167], v[60:63]
	v_mfma_f32_16x16x32_bf16 v[56:59], v[156:159], v[164:167], v[56:59]
	v_mfma_f32_16x16x32_bf16 v[52:55], v[148:151], v[172:175], v[52:55]
	v_mfma_f32_16x16x32_bf16 v[44:47], v[156:159], v[172:175], v[44:47]
	v_mfma_f32_16x16x32_bf16 v[36:39], v[148:151], v[180:183], v[36:39]
	v_mfma_f32_16x16x32_bf16 v[28:31], v[156:159], v[180:183], v[28:31]
	v_mfma_f32_16x16x32_bf16 v[20:23], v[148:151], v[188:191], v[20:23]
	v_mfma_f32_16x16x32_bf16 v[12:15], v[156:159], v[188:191], v[12:15]
	s_setprio 0
	s_barrier
	s_add_u32 s66, s66, 0x20000
	s_addc_u32 s67, s67, 0
	s_add_i32 s0, s1, s24
	v_lshl_add_u64 v[134:135], s[66:67], 0, v[146:147]
	s_mov_b32 m0, s0
	s_nop 0
	global_load_lds_dwordx4 v[134:135], off
	v_lshl_add_u64 v[134:135], s[66:67], 0, v[128:129]
	s_add_i32 m0, s0, 0x2000
	s_nop 0
	global_load_lds_dwordx4 v[134:135], off
	s_waitcnt vmcnt(6)
	s_barrier
	s_setprio 1
	v_mfma_f32_16x16x32_bf16 v[48:51], v[192:195], v[160:163], v[48:51]
	v_mfma_f32_16x16x32_bf16 v[40:43], v[200:203], v[160:163], v[40:43]
	v_mfma_f32_16x16x32_bf16 v[32:35], v[192:195], v[168:171], v[32:35]
	v_mfma_f32_16x16x32_bf16 v[24:27], v[200:203], v[168:171], v[24:27]
	v_mfma_f32_16x16x32_bf16 v[16:19], v[192:195], v[176:179], v[16:19]
	v_mfma_f32_16x16x32_bf16 v[8:11], v[200:203], v[176:179], v[8:11]
	v_mfma_f32_16x16x32_bf16 v[4:7], v[192:195], v[184:187], v[4:7]
	v_mfma_f32_16x16x32_bf16 v[0:3], v[200:203], v[184:187], v[0:3]
	v_mfma_f32_16x16x32_bf16 v[48:51], v[196:199], v[164:167], v[48:51]
	v_mfma_f32_16x16x32_bf16 v[40:43], v[204:207], v[164:167], v[40:43]
	v_mfma_f32_16x16x32_bf16 v[32:35], v[196:199], v[172:175], v[32:35]
	v_mfma_f32_16x16x32_bf16 v[24:27], v[204:207], v[172:175], v[24:27]
	v_mfma_f32_16x16x32_bf16 v[16:19], v[196:199], v[180:183], v[16:19]
	v_mfma_f32_16x16x32_bf16 v[8:11], v[204:207], v[180:183], v[8:11]
	v_mfma_f32_16x16x32_bf16 v[4:7], v[196:199], v[188:191], v[4:7]
	v_mfma_f32_16x16x32_bf16 v[0:3], v[204:207], v[188:191], v[0:3]
	s_setprio 0
	s_add_i32 s6, s6, 2
	s_addk_i32 s56, 0x100
	s_addk_i32 s7, 0x100
	s_add_i32 s1, s56, 0xffffff80
	s_and_b32 s0, s7, 0x380
	s_and_b32 s1, s1, 0x380
	s_add_u32 s57, s64, s1
	s_addc_u32 s66, s65, 0
	s_add_u32 s1, s62, s1
	s_addc_u32 s67, s63, 0
	s_and_b32 s68, s56, 0x380
	s_add_u32 s80, s64, s68
	s_addc_u32 s69, s65, 0
	s_add_u32 s97, s62, s68
	s_addc_u32 vcc_lo, s63, 0
	s_cmp_eq_u32 s6, 4
	s_cselect_b32 s71, s83, s66
	s_cselect_b32 s70, s47, s57
	s_cselect_b32 s73, s87, s67
	s_cselect_b32 s72, s86, s1
	s_cselect_b32 s69, s94, s69
	s_cselect_b32 s68, s33, s80
	s_cselect_b32 s67, s5, vcc_lo
	s_cselect_b32 s66, s96, s97
	s_cmp_gt_u32 s6, 5
	s_barrier
	s_cbranch_scc0 .LBB0_104
; DI unsigned pk2(float lo, float hi) { unsigned r; asm("v_cvt_pk_bf16_f32 %0, %1, %2" : "=v"(r) : "v"(lo), "v"(hi)); return r; }
; #define G_WAIT_V(n) asm volatile("s_waitcnt vmcnt(" #n ")" ::: "memory")
; #define G_BAR __builtin_amdgcn_s_barrier()
; template <class J>
; DI void gemm_phase(LAS unsigned char* lds, const J& job) {
;     ...
;     cur = nxt; cA = nA; cB = nB; ++ui;
;   }
;   G_WAIT_V(0);
;   if (wr == 0) G_BAR;
;   G_BAR;
;   DI void epi(const Acc& acc, const Unit& u, int wr, int wc, int fr, int fq) const {
; #pragma unroll
;     for (int ai = 0; ai < 2; ++ai)
; #pragma unroll
;       for (int m = 0; m < 4; ++m) {
;         const int row = u.pm * 256 + ai * HALF + wr * 64 + m * 16 + fr;
; #pragma unroll
;         for (int bj = 0; bj < 2; ++bj) {
;           const int col = u.pn * 256 + bj * HALF + wc * 32 + 8 * fq;
;           const f32x4 v0 = acc[ai][bj][m][0], v1 = acc[ai][bj][m][1];
;           u32x4 o; o.x = pk2(v0.x, v0.y); o.y = pk2(v0.z, v0.w); o.z = pk2(v1.x, v1.y); o.w = pk2(v1.z, v1.w);
;           *(u32x4*)(Z + (size_t)row * NGATE + col) = o;
;         }
;       }
;   }
	v_mov_b32_e32 v135, v137
	v_mov_b32_e32 v134, v136
	s_lshl_b32 s0, s22, 8
	s_add_i32 s0, s0, s44
	v_add_u32_e32 v134, s0, v134
	s_lshl_b32 s0, s46, 8
	s_or_b32 s0, s0, s45
	v_cvt_pk_bf16_f32 v68, v68, v69
	v_cvt_pk_bf16_f32 v69, v70, v71
	v_cvt_pk_bf16_f32 v70, v64, v65
	v_add_u32_e32 v64, 0x80, v134
	v_lshl_add_u32 v140, v135, 3, s0
	v_ashrrev_i32_e32 v135, 31, v134
	v_ashrrev_i32_e32 v65, 31, v64
	v_lshlrev_b64 v[142:143], 14, v[134:135]
	v_ashrrev_i32_e32 v141, 31, v140
	v_lshlrev_b64 v[64:65], 14, v[64:65]
	v_cvt_pk_bf16_f32 v124, v124, v125
	v_cvt_pk_bf16_f32 v125, v126, v127
	v_cvt_pk_bf16_f32 v126, v120, v121
	v_cvt_pk_bf16_f32 v127, v122, v123
	v_lshl_add_u64 v[122:123], s[26:27], 0, v[142:143]
	v_lshlrev_b64 v[120:121], 1, v[140:141]
	v_cvt_pk_bf16_f32 v112, v112, v113
	v_cvt_pk_bf16_f32 v113, v114, v115
	v_cvt_pk_bf16_f32 v114, v104, v105
	v_add_u32_e32 v104, 16, v134
	v_cvt_pk_bf16_f32 v60, v60, v61
	v_cvt_pk_bf16_f32 v61, v62, v63
	v_cvt_pk_bf16_f32 v62, v56, v57
	v_lshl_add_u64 v[56:57], s[26:27], 0, v[64:65]
	v_cvt_pk_bf16_f32 v48, v48, v49
	v_cvt_pk_bf16_f32 v49, v50, v51
	v_cvt_pk_bf16_f32 v50, v40, v41
	v_add_u32_e32 v40, 0x90, v134
	v_lshl_add_u64 v[122:123], v[122:123], 0, v[120:121]
	v_ashrrev_i32_e32 v105, 31, v104
	v_lshl_add_u64 v[56:57], v[56:57], 0, v[120:121]
	v_ashrrev_i32_e32 v41, 31, v40
	v_cvt_pk_bf16_f32 v115, v106, v107
	global_store_dwordx4 v[122:123], v[112:115], off offset:256
	v_cvt_pk_bf16_f32 v51, v42, v43
	global_store_dwordx4 v[56:57], v[48:51], off offset:256
	v_cvt_pk_bf16_f32 v106, v108, v109
	v_cvt_pk_bf16_f32 v96, v96, v97
	v_cvt_pk_bf16_f32 v97, v98, v99
	s_nop 0
	v_lshlrev_b64 v[112:113], 14, v[104:105]
	v_lshl_add_u64 v[108:109], s[26:27], 0, v[112:113]
	v_lshlrev_b64 v[48:49], 14, v[40:41]
	v_cvt_pk_bf16_f32 v98, v88, v89
	v_add_u32_e32 v88, 32, v134
	v_cvt_pk_bf16_f32 v42, v44, v45
	v_lshl_add_u64 v[44:45], s[26:27], 0, v[48:49]
	v_cvt_pk_bf16_f32 v32, v32, v33
	v_cvt_pk_bf16_f32 v33, v34, v35
	v_cvt_pk_bf16_f32 v34, v24, v25
	v_add_u32_e32 v24, 0xa0, v134
	v_lshl_add_u64 v[108:109], v[108:109], 0, v[120:121]
	v_ashrrev_i32_e32 v89, 31, v88
	v_lshl_add_u64 v[44:45], v[44:45], 0, v[120:121]
	v_ashrrev_i32_e32 v25, 31, v24
	v_cvt_pk_bf16_f32 v99, v90, v91
	global_store_dwordx4 v[108:109], v[96:99], off offset:256
	v_cvt_pk_bf16_f32 v35, v26, v27
	global_store_dwordx4 v[44:45], v[32:35], off offset:256
	v_cvt_pk_bf16_f32 v90, v92, v93
	v_cvt_pk_bf16_f32 v80, v80, v81
	v_cvt_pk_bf16_f32 v81, v82, v83
	s_nop 0
	v_lshlrev_b64 v[96:97], 14, v[88:89]
	v_lshl_add_u64 v[92:93], s[26:27], 0, v[96:97]
	v_lshlrev_b64 v[32:33], 14, v[24:25]
	v_cvt_pk_bf16_f32 v82, v72, v73
	v_add_u32_e32 v72, 48, v134
	v_cvt_pk_bf16_f32 v26, v28, v29
	v_lshl_add_u64 v[28:29], s[26:27], 0, v[32:33]
	v_cvt_pk_bf16_f32 v16, v16, v17
	v_cvt_pk_bf16_f32 v17, v18, v19
	v_cvt_pk_bf16_f32 v18, v8, v9
	v_add_u32_e32 v8, 0xb0, v134
	v_lshl_add_u64 v[92:93], v[92:93], 0, v[120:121]
	v_ashrrev_i32_e32 v73, 31, v72
	v_lshl_add_u64 v[28:29], v[28:29], 0, v[120:121]
	v_ashrrev_i32_e32 v9, 31, v8
	v_cvt_pk_bf16_f32 v83, v74, v75
	global_store_dwordx4 v[92:93], v[80:83], off offset:256
	v_cvt_pk_bf16_f32 v19, v10, v11
	global_store_dwordx4 v[28:29], v[16:19], off offset:256
	v_cvt_pk_bf16_f32 v74, v76, v77
	v_cvt_pk_bf16_f32 v10, v12, v13
	s_and_b64 vcc, exec, s[12:13]
	v_lshlrev_b64 v[80:81], 14, v[72:73]
	v_lshlrev_b64 v[16:17], 14, v[8:9]
	v_lshl_add_u64 v[76:77], s[26:27], 0, v[80:81]
	v_lshl_add_u64 v[12:13], s[26:27], 0, v[16:17]
	v_lshl_add_u64 v[76:77], v[76:77], 0, v[120:121]
	v_lshl_add_u64 v[12:13], v[12:13], 0, v[120:121]
	s_mov_b32 s46, s8
	s_mov_b32 s22, s16
	s_mov_b64 s[62:63], s[20:21]
	s_mov_b64 s[64:65], s[18:19]
	global_store_dwordx4 v[122:123], v[124:127], off
	v_cvt_pk_bf16_f32 v104, v116, v117
	v_cvt_pk_bf16_f32 v105, v118, v119
	v_cvt_pk_bf16_f32 v107, v110, v111
	global_store_dwordx4 v[108:109], v[104:107], off
	v_cvt_pk_bf16_f32 v88, v100, v101
	v_cvt_pk_bf16_f32 v89, v102, v103
	v_cvt_pk_bf16_f32 v91, v94, v95
	global_store_dwordx4 v[92:93], v[88:91], off
	v_cvt_pk_bf16_f32 v72, v84, v85
	v_cvt_pk_bf16_f32 v73, v86, v87
	v_cvt_pk_bf16_f32 v75, v78, v79
	global_store_dwordx4 v[76:77], v[72:75], off
	v_cvt_pk_bf16_f32 v71, v66, v67
	global_store_dwordx4 v[76:77], v[68:71], off offset:256
	v_cvt_pk_bf16_f32 v63, v58, v59
	global_store_dwordx4 v[56:57], v[60:63], off
	v_cvt_pk_bf16_f32 v40, v52, v53
	v_cvt_pk_bf16_f32 v41, v54, v55
	v_cvt_pk_bf16_f32 v43, v46, v47
	global_store_dwordx4 v[44:45], v[40:43], off
	v_cvt_pk_bf16_f32 v24, v36, v37
	v_cvt_pk_bf16_f32 v25, v38, v39
	v_cvt_pk_bf16_f32 v27, v30, v31
	global_store_dwordx4 v[28:29], v[24:27], off
	v_cvt_pk_bf16_f32 v8, v20, v21
	v_cvt_pk_bf16_f32 v9, v22, v23
	v_cvt_pk_bf16_f32 v11, v14, v15
	global_store_dwordx4 v[12:13], v[8:11], off
	v_cvt_pk_bf16_f32 v4, v4, v5
	v_cvt_pk_bf16_f32 v5, v6, v7
	v_cvt_pk_bf16_f32 v6, v0, v1
	v_cvt_pk_bf16_f32 v7, v2, v3
	global_store_dwordx4 v[12:13], v[4:7], off offset:256
	s_cbranch_vccz .LBB0_101
	s_waitcnt vmcnt(0)
	v_readlane_b32 s44, v255, 6
	s_cmpk_gt_u32 s4, 0xff
	v_readlane_b32 s45, v255, 7
	s_cbranch_scc1 .LBB0_108
	s_barrier

;   DI const char* aptr(const Unit& u) const { return (const char*)(h + (size_t)u.pm * 256 * DM); }
;   DI const char* bptr(const Unit& u) const { return (const char*)(winT + (size_t)u.pn * 256 * DM); }
;   DI bool next(int i, Unit& u) const { const int L = i * G + c; if (L >= nunits) return false; u.kind = 0; decode_unit(L, 65, 32, u.pm, u.pn); return true; }
;   DI const char* aptr(const Unit& u) const { return (const char*)(y + (size_t)u.pm * 256 * DM + (u.pn >> 3) * 512); }
;   DI const char* bptr(const Unit& u) const { return (const char*)(wbT + (size_t)u.pn * 256 * 512); }
;   DI const char* aptr(const Unit& u) const { return (const char*)(h + (size_t)u.pm * 256 * DM); }
;   DI const char* bptr(const Unit& u) const { return (const char*)(wgT + (size_t)u.pn * 64 * DM); }
;   DI const char* aptr(const Unit& u) const { return (const char*)(mixed + (size_t)u.pm * 256 * DM); }
;   DI const char* bptr(const Unit& u) const { return (const char*)(woutT + (size_t)u.pn * 256 * DM); }
; template <class J>
; DI void gemm_phase(LAS unsigned char* lds, const J& job) {
;     ...
;     const bool has_next = job.next(ui + 1, nxt);
;     const char* nA = has_next ? job.aptr(nxt) : cA; const char* nB = has_next ? job.bptr(nxt) : cB;
;     for (int t = 0; t < nt; t += 2) {
;       const bool last = (t == nt - 2);
;       const char* a1 = cA + G_KT(t + 1);
;       const char* a2 = last ? nA + G_KT(0) : cA + G_KT(t + 2); const char* b2 = last ? nB + G_KT(0) : cB + G_KT(t + 2);
;       const char* a3 = last ? nA + G_KT(1) : cA + G_KT(t + 3); const char* b3 = last ? nB + G_KT(1) : cB + G_KT(t + 3);
;     ...
; #pragma unroll
;     for (int a = 0; a < 2; ++a)
; #pragma unroll
;       for (int b = 0; b < 2; ++b)
; #pragma unroll
;         for (int m = 0; m < 4; ++m)
; #pragma unroll
;           for (int n = 0; n < 2; ++n) acc[a][b][m][n] = (f32x4){0.f, 0.f, 0.f, 0.f};
.LBB0_281:
	s_ashr_i32 s19, s18, 31
	s_lshl_b64 s[6:7], s[18:19], 20
	s_add_u32 s22, s58, s6
	s_addc_u32 s23, s59, s7
	s_ashr_i32 s21, s20, 31
	s_lshl_b64 s[6:7], s[20:21], 20
	s_add_u32 s62, s12, s6
	s_addc_u32 s63, s13, s7
	s_add_u32 s9, s68, 0x80000
	s_addc_u32 s19, s69, 0
	s_and_b64 s[6:7], s[70:71], exec
	s_cselect_b32 s7, s22, s68
	s_cselect_b32 s0, s63, s67
	s_cselect_b32 s1, s62, s66
	s_cselect_b32 s6, s23, s69
	s_add_u32 s21, s7, s14
	s_addc_u32 s46, s6, 0
	s_add_u32 s47, s1, s14
	s_addc_u32 s96, s0, 0
	s_add_u32 s33, s7, s44
	s_addc_u32 s97, s6, 0
	s_add_u32 vcc_lo, s1, s44
	v_mov_b32_e32 v0, 0
	s_addc_u32 vcc_hi, s0, 0
	s_mov_b32 s6, -2
	s_mov_b32 s7, s94
	s_mov_b32 s56, s87
	v_mov_b32_e32 v1, v0
	v_mov_b32_e32 v2, v0
	v_mov_b32_e32 v3, v0
	v_mov_b32_e32 v4, v0
	v_mov_b32_e32 v5, v0
	v_mov_b32_e32 v6, v0
	v_mov_b32_e32 v7, v0
	v_mov_b32_e32 v16, v0
	v_mov_b32_e32 v17, v0
	v_mov_b32_e32 v18, v0
	v_mov_b32_e32 v19, v0
	v_mov_b32_e32 v20, v0
	v_mov_b32_e32 v21, v0
	v_mov_b32_e32 v22, v0
	v_mov_b32_e32 v23, v0
	v_mov_b32_e32 v32, v0
	v_mov_b32_e32 v33, v0
	v_mov_b32_e32 v34, v0
	v_mov_b32_e32 v35, v0
	v_mov_b32_e32 v36, v0
	v_mov_b32_e32 v37, v0
	v_mov_b32_e32 v38, v0
	v_mov_b32_e32 v39, v0
	v_mov_b32_e32 v48, v0
	v_mov_b32_e32 v49, v0
	v_mov_b32_e32 v50, v0
	v_mov_b32_e32 v51, v0
	v_mov_b32_e32 v52, v0
	v_mov_b32_e32 v53, v0
	v_mov_b32_e32 v54, v0
	v_mov_b32_e32 v55, v0
	v_mov_b32_e32 v8, v0
	v_mov_b32_e32 v9, v0
	v_mov_b32_e32 v10, v0
	v_mov_b32_e32 v11, v0
	v_mov_b32_e32 v12, v0
	v_mov_b32_e32 v13, v0
	v_mov_b32_e32 v14, v0
	v_mov_b32_e32 v15, v0
	v_mov_b32_e32 v24, v0
	v_mov_b32_e32 v25, v0
	v_mov_b32_e32 v26, v0
	v_mov_b32_e32 v27, v0
	v_mov_b32_e32 v28, v0
	v_mov_b32_e32 v29, v0
	v_mov_b32_e32 v30, v0
	v_mov_b32_e32 v31, v0
	v_mov_b32_e32 v40, v0
	v_mov_b32_e32 v41, v0
	v_mov_b32_e32 v42, v0
	v_mov_b32_e32 v43, v0
	v_mov_b32_e32 v44, v0
	v_mov_b32_e32 v45, v0
	v_mov_b32_e32 v46, v0
	v_mov_b32_e32 v47, v0
	v_mov_b32_e32 v56, v0
	v_mov_b32_e32 v57, v0
	v_mov_b32_e32 v58, v0
	v_mov_b32_e32 v59, v0
	v_mov_b32_e32 v60, v0
	v_mov_b32_e32 v61, v0
	v_mov_b32_e32 v62, v0
	v_mov_b32_e32 v63, v0
	v_mov_b32_e32 v64, v0
	v_mov_b32_e32 v65, v0
	v_mov_b32_e32 v66, v0
	v_mov_b32_e32 v67, v0
	v_mov_b32_e32 v68, v0
	v_mov_b32_e32 v69, v0
	v_mov_b32_e32 v70, v0
	v_mov_b32_e32 v71, v0
	v_mov_b32_e32 v80, v0
	v_mov_b32_e32 v81, v0
	v_mov_b32_e32 v82, v0
	v_mov_b32_e32 v83, v0
	v_mov_b32_e32 v84, v0
	v_mov_b32_e32 v85, v0
	v_mov_b32_e32 v86, v0
	v_mov_b32_e32 v87, v0
	v_mov_b32_e32 v96, v0
	v_mov_b32_e32 v97, v0
	v_mov_b32_e32 v98, v0
	v_mov_b32_e32 v99, v0
	v_mov_b32_e32 v100, v0
	v_mov_b32_e32 v101, v0
	v_mov_b32_e32 v102, v0
	v_mov_b32_e32 v103, v0
	v_mov_b32_e32 v112, v0
	v_mov_b32_e32 v113, v0
	v_mov_b32_e32 v114, v0
	v_mov_b32_e32 v115, v0
	v_mov_b32_e32 v116, v0
	v_mov_b32_e32 v117, v0
	v_mov_b32_e32 v118, v0
	v_mov_b32_e32 v119, v0
	v_mov_b32_e32 v72, v0
	v_mov_b32_e32 v73, v0
	v_mov_b32_e32 v74, v0
	v_mov_b32_e32 v75, v0
	v_mov_b32_e32 v76, v0
	v_mov_b32_e32 v77, v0
	v_mov_b32_e32 v78, v0
	v_mov_b32_e32 v79, v0
	v_mov_b32_e32 v88, v0
	v_mov_b32_e32 v89, v0
	v_mov_b32_e32 v90, v0
	v_mov_b32_e32 v91, v0
	v_mov_b32_e32 v92, v0
	v_mov_b32_e32 v93, v0
	v_mov_b32_e32 v94, v0
	v_mov_b32_e32 v95, v0
	v_mov_b32_e32 v104, v0
	v_mov_b32_e32 v105, v0
	v_mov_b32_e32 v106, v0
	v_mov_b32_e32 v107, v0
	v_mov_b32_e32 v108, v0
	v_mov_b32_e32 v109, v0
	v_mov_b32_e32 v110, v0
	v_mov_b32_e32 v111, v0
	v_mov_b32_e32 v120, v0
	v_mov_b32_e32 v121, v0
	v_mov_b32_e32 v122, v0
	v_mov_b32_e32 v123, v0
	v_mov_b32_e32 v124, v0
	v_mov_b32_e32 v125, v0
	v_mov_b32_e32 v126, v0
	v_mov_b32_e32 v127, v0
	s_add_i32 s1, s56, 0xffffff80
	s_and_b32 s0, s7, 0xf80
	s_and_b32 s1, s1, 0xf00
	s_add_u32 s10, s68, s1
	s_addc_u32 s11, s69, 0
	s_add_u32 s1, s66, s1
	s_addc_u32 s57, s67, 0
	s_and_b32 s70, s56, 0xf80
	s_add_u32 s71, s68, s70
	s_addc_u32 s72, s69, 0
	s_add_u32 s70, s66, s70
	s_addc_u32 s80, s67, 0
	s_cmp_eq_u32 s6, 28
	s_cselect_b32 s75, s46, s11
	s_cselect_b32 s74, s21, s10
	s_cselect_b32 s77, s96, s57
	s_cselect_b32 s76, s47, s1
	s_cselect_b32 s73, s97, s72
	s_cselect_b32 s72, s33, s71
	s_cselect_b32 s71, vcc_hi, s80
	s_cselect_b32 s70, vcc_lo, s70
.LBB0_282:
	s_add_i32 s1, s84, 0x100
	v_add_u32_e32 v142, s1, v150
	ds_read_b128 v[134:137], v142
	ds_read_b128 v[138:141], v142 offset:1024
	ds_read_b128 v[152:155], v142 offset:2048
	ds_read_b128 v[156:159], v142 offset:3072
	s_add_u32 s10, s9, s0
	s_addc_u32 s11, s19, 0
	v_lshl_add_u64 v[142:143], s[10:11], 0, v[128:129]
	s_add_i32 m0, s15, 0xc000
	ds_read_b128 v[160:163], v151
	ds_read_b128 v[164:167], v151 offset:1024
	ds_read_b128 v[168:171], v151 offset:2048
	ds_read_b128 v[172:175], v151 offset:3072
	ds_read_b128 v[176:179], v151 offset:4096
	ds_read_b128 v[180:183], v151 offset:5120
	ds_read_b128 v[184:187], v151 offset:6144
	ds_read_b128 v[188:191], v151 offset:7168
	global_load_lds_dwordx4 v[142:143], off
	v_lshl_add_u64 v[142:143], s[10:11], 0, v[130:131]
	s_add_i32 m0, s15, 0xe000
	s_nop 0
	global_load_lds_dwordx4 v[142:143], off
	s_waitcnt lgkmcnt(8)
	s_barrier
; #define G_STAGE(bufoff, gbase, voff) do { _Pragma("unroll") for (int _i = 0; _i < 2; ++_i) \
;         __builtin_amdgcn_global_load_lds((const unsigned*)((const char*)(gbase) + (voff)[_i]), (LAS unsigned*)(lds + (bufoff) + ldsw + _i * 8192), 16, 0, 0); } while (0)
; #define G_LDA(dst, b, h) do { _Pragma("unroll") for (int m = 0; m < 4; ++m) _Pragma("unroll") for (int k = 0; k < 2; ++k) dst[m][k] = *(const LAS bf16x8*)(lds + G_SA(b, h) + aoff + m * 2048 + k * 1024); } while (0)
; #define G_LDB(dst, b, h) do { _Pragma("unroll") for (int n = 0; n < 2; ++n) _Pragma("unroll") for (int k = 0; k < 2; ++k) dst[n][k] = *(const LAS bf16x8*)(lds + G_SB(b, h) + boff + n * 2048 + k * 1024); } while (0)
; #define G_MMA(ai, bj, At, Bt) do { __builtin_amdgcn_s_setprio(1); _Pragma("unroll") for (int m = 0; m < 4; ++m) _Pragma("unroll") for (int n = 0; n < 2; ++n) _Pragma("unroll") for (int k = 0; k < 2; ++k) \
;         acc[ai][bj][m][n] = __builtin_amdgcn_mfma_f32_16x16x32_bf16(Bt[n][k], At[m][k], acc[ai][bj][m][n], 0, 0, 0); __builtin_amdgcn_s_setprio(0); } while (0)
; #define G_WAIT_V(n) asm volatile("s_waitcnt vmcnt(" #n ")" ::: "memory")
; #define G_WAIT_L(n) asm volatile("s_waitcnt lgkmcnt(" #n ")" ::: "memory")
; #define G_BAR __builtin_amdgcn_s_barrier()
; #define G_SCHED __builtin_amdgcn_sched_barrier(0)
; template <class J>
; DI void gemm_phase(LAS unsigned char* lds, const J& job) {
;     ...
;       G_WAIT_L(8); G_BAR; G_WAIT_L(0); G_MMA(0, 0, At, B0); G_BAR; G_SCHED;
;       G_LDB(B1, 0, 1); G_STAGE(G_SB(0, 0), b2, voffB);
;       G_BAR; G_WAIT_L(0); G_MMA(0, 1, At, B1); G_BAR;
;       G_LDA(At, 0, 1); G_STAGE(G_SA(0, 0), a2, voffA);
;       G_BAR; G_WAIT_L(0); G_MMA(1, 0, At, B0); G_BAR; G_SCHED;
;       G_STAGE(G_SB(0, 1), b2 + hstepB, voffB);
;       G_WAIT_V(6); G_BAR; G_MMA(1, 1, At, B1); G_BAR;
	s_waitcnt lgkmcnt(0)
	s_setprio 1
	s_waitcnt lgkmcnt(0)
	v_mfma_f32_16x16x32_bf16 v[124:127], v[134:137], v[160:163], v[124:127]
	v_mfma_f32_16x16x32_bf16 v[120:123], v[152:155], v[160:163], v[120:123]
	v_mfma_f32_16x16x32_bf16 v[108:111], v[134:137], v[168:171], v[108:111]
	v_mfma_f32_16x16x32_bf16 v[104:107], v[152:155], v[168:171], v[104:107]
	v_mfma_f32_16x16x32_bf16 v[92:95], v[134:137], v[176:179], v[92:95]
	v_mfma_f32_16x16x32_bf16 v[88:91], v[152:155], v[176:179], v[88:91]
	v_mfma_f32_16x16x32_bf16 v[76:79], v[134:137], v[184:187], v[76:79]
	v_mfma_f32_16x16x32_bf16 v[72:75], v[152:155], v[184:187], v[72:75]
	v_mfma_f32_16x16x32_bf16 v[124:127], v[138:141], v[164:167], v[124:127]
	v_mfma_f32_16x16x32_bf16 v[120:123], v[156:159], v[164:167], v[120:123]
	v_mfma_f32_16x16x32_bf16 v[108:111], v[138:141], v[172:175], v[108:111]
	v_mfma_f32_16x16x32_bf16 v[104:107], v[156:159], v[172:175], v[104:107]
	v_mfma_f32_16x16x32_bf16 v[92:95], v[138:141], v[180:183], v[92:95]
	v_mfma_f32_16x16x32_bf16 v[88:91], v[156:159], v[180:183], v[88:91]
	v_mfma_f32_16x16x32_bf16 v[76:79], v[138:141], v[188:191], v[76:79]
	v_mfma_f32_16x16x32_bf16 v[72:75], v[156:159], v[188:191], v[72:75]
	s_setprio 0
	s_barrier
	s_add_i32 s0, s85, 0x100
	v_add_u32_e32 v142, s0, v150
	s_add_i32 s1, s1, s5
	ds_read_b128 v[192:195], v142
	ds_read_b128 v[196:199], v142 offset:1024
	ds_read_b128 v[200:203], v142 offset:2048
	ds_read_b128 v[204:207], v142 offset:3072
	v_lshl_add_u64 v[142:143], s[76:77], 0, v[146:147]
	s_mov_b32 m0, s1
	s_nop 0
	global_load_lds_dwordx4 v[142:143], off
	v_lshl_add_u64 v[142:143], s[76:77], 0, v[132:133]
	s_add_i32 m0, s1, 0x2000
	s_nop 0
	global_load_lds_dwordx4 v[142:143], off
	s_barrier
	s_waitcnt lgkmcnt(0)
	s_setprio 1
	s_waitcnt lgkmcnt(0)
	v_mfma_f32_16x16x32_bf16 v[116:119], v[192:195], v[160:163], v[116:119]
	v_mfma_f32_16x16x32_bf16 v[112:115], v[200:203], v[160:163], v[112:115]
	v_mfma_f32_16x16x32_bf16 v[100:103], v[192:195], v[168:171], v[100:103]
	v_mfma_f32_16x16x32_bf16 v[96:99], v[200:203], v[168:171], v[96:99]
	v_mfma_f32_16x16x32_bf16 v[84:87], v[192:195], v[176:179], v[84:87]
	v_mfma_f32_16x16x32_bf16 v[80:83], v[200:203], v[176:179], v[80:83]
	v_mfma_f32_16x16x32_bf16 v[68:71], v[192:195], v[184:187], v[68:71]
	v_mfma_f32_16x16x32_bf16 v[64:67], v[200:203], v[184:187], v[64:67]
	v_mfma_f32_16x16x32_bf16 v[116:119], v[196:199], v[164:167], v[116:119]
	v_mfma_f32_16x16x32_bf16 v[112:115], v[204:207], v[164:167], v[112:115]
	v_mfma_f32_16x16x32_bf16 v[100:103], v[196:199], v[172:175], v[100:103]
	v_mfma_f32_16x16x32_bf16 v[96:99], v[204:207], v[172:175], v[96:99]
	v_mfma_f32_16x16x32_bf16 v[84:87], v[196:199], v[180:183], v[84:87]
	v_mfma_f32_16x16x32_bf16 v[80:83], v[204:207], v[180:183], v[80:83]
	v_mfma_f32_16x16x32_bf16 v[68:71], v[196:199], v[188:191], v[68:71]
	v_mfma_f32_16x16x32_bf16 v[64:67], v[204:207], v[188:191], v[64:67]
	s_setprio 0
	s_mov_b32 m0, s15
	v_lshl_add_u64 v[142:143], s[74:75], 0, v[128:129]
	s_barrier
	ds_read_b128 v[160:163], v151 offset:16384
	ds_read_b128 v[164:167], v151 offset:17408
	ds_read_b128 v[168:171], v151 offset:18432
	ds_read_b128 v[172:175], v151 offset:19456
	ds_read_b128 v[176:179], v151 offset:20480
	ds_read_b128 v[180:183], v151 offset:21504
	ds_read_b128 v[184:187], v151 offset:22528
	ds_read_b128 v[188:191], v151 offset:23552
	global_load_lds_dwordx4 v[142:143], off
	v_lshl_add_u64 v[142:143], s[74:75], 0, v[130:131]
	s_mov_b32 m0, s24
	s_nop 0
	global_load_lds_dwordx4 v[142:143], off
	s_barrier
	s_waitcnt lgkmcnt(0)
	s_setprio 1
	s_waitcnt lgkmcnt(0)
	v_mfma_f32_16x16x32_bf16 v[60:63], v[134:137], v[160:163], v[60:63]
	v_mfma_f32_16x16x32_bf16 v[56:59], v[152:155], v[160:163], v[56:59]
	v_mfma_f32_16x16x32_bf16 v[44:47], v[134:137], v[168:171], v[44:47]
	v_mfma_f32_16x16x32_bf16 v[40:43], v[152:155], v[168:171], v[40:43]
	v_mfma_f32_16x16x32_bf16 v[28:31], v[134:137], v[176:179], v[28:31]
	v_mfma_f32_16x16x32_bf16 v[24:27], v[152:155], v[176:179], v[24:27]
	v_mfma_f32_16x16x32_bf16 v[12:15], v[134:137], v[184:187], v[12:15]
	v_mfma_f32_16x16x32_bf16 v[8:11], v[152:155], v[184:187], v[8:11]
	v_mfma_f32_16x16x32_bf16 v[60:63], v[138:141], v[164:167], v[60:63]
	v_mfma_f32_16x16x32_bf16 v[56:59], v[156:159], v[164:167], v[56:59]
	v_mfma_f32_16x16x32_bf16 v[44:47], v[138:141], v[172:175], v[44:47]
	v_mfma_f32_16x16x32_bf16 v[40:43], v[156:159], v[172:175], v[40:43]
	v_mfma_f32_16x16x32_bf16 v[28:31], v[138:141], v[180:183], v[28:31]
	v_mfma_f32_16x16x32_bf16 v[24:27], v[156:159], v[180:183], v[24:27]
	v_mfma_f32_16x16x32_bf16 v[12:15], v[138:141], v[188:191], v[12:15]
	v_mfma_f32_16x16x32_bf16 v[8:11], v[156:159], v[188:191], v[8:11]
	s_setprio 0
	s_barrier
	s_add_u32 s10, s76, 0x80000
	s_addc_u32 s11, s77, 0
	s_add_i32 s0, s0, s5
	v_lshl_add_u64 v[134:135], s[10:11], 0, v[146:147]
	s_mov_b32 m0, s0
	s_nop 0
	global_load_lds_dwordx4 v[134:135], off
	v_lshl_add_u64 v[134:135], s[10:11], 0, v[132:133]
	s_add_i32 m0, s0, 0x2000
	s_nop 0
	global_load_lds_dwordx4 v[134:135], off
	s_waitcnt vmcnt(6)
	s_barrier
; #define G_STAGE(bufoff, gbase, voff) do { _Pragma("unroll") for (int _i = 0; _i < 2; ++_i) \
;         __builtin_amdgcn_global_load_lds((const unsigned*)((const char*)(gbase) + (voff)[_i]), (LAS unsigned*)(lds + (bufoff) + ldsw + _i * 8192), 16, 0, 0); } while (0)
; #define G_LDA(dst, b, h) do { _Pragma("unroll") for (int m = 0; m < 4; ++m) _Pragma("unroll") for (int k = 0; k < 2; ++k) dst[m][k] = *(const LAS bf16x8*)(lds + G_SA(b, h) + aoff + m * 2048 + k * 1024); } while (0)
; #define G_LDB(dst, b, h) do { _Pragma("unroll") for (int n = 0; n < 2; ++n) _Pragma("unroll") for (int k = 0; k < 2; ++k) dst[n][k] = *(const LAS bf16x8*)(lds + G_SB(b, h) + boff + n * 2048 + k * 1024); } while (0)
; #define G_MMA(ai, bj, At, Bt) do { __builtin_amdgcn_s_setprio(1); _Pragma("unroll") for (int m = 0; m < 4; ++m) _Pragma("unroll") for (int n = 0; n < 2; ++n) _Pragma("unroll") for (int k = 0; k < 2; ++k) \
;         acc[ai][bj][m][n] = __builtin_amdgcn_mfma_f32_16x16x32_bf16(Bt[n][k], At[m][k], acc[ai][bj][m][n], 0, 0, 0); __builtin_amdgcn_s_setprio(0); } while (0)
; #define G_WAIT_V(n) asm volatile("s_waitcnt vmcnt(" #n ")" ::: "memory")
; #define G_WAIT_L(n) asm volatile("s_waitcnt lgkmcnt(" #n ")" ::: "memory")
; #define G_BAR __builtin_amdgcn_s_barrier()
; #define G_SCHED __builtin_amdgcn_sched_barrier(0)
; template <class J>
; DI void gemm_phase(LAS unsigned char* lds, const J& job) {
;     ...
;       G_WAIT_V(6); G_BAR; G_MMA(1, 1, At, B1); G_BAR;
;       G_LDB(B0, 1, 0); G_SCHED; G_LDA(At, 1, 0); G_STAGE(G_SA(0, 1), a2 + hstepA, voffA);
;       G_WAIT_L(8); G_BAR; G_WAIT_L(0); G_MMA(0, 0, At, B0); G_BAR; G_SCHED;
;       G_LDB(B1, 1, 1); G_STAGE(G_SB(1, 0), b3, voffB);
;       G_BAR; G_WAIT_L(0); G_MMA(0, 1, At, B1); G_BAR;
;       G_LDA(At, 1, 1); G_STAGE(G_SA(1, 0), a3, voffA);
	s_setprio 1
	v_mfma_f32_16x16x32_bf16 v[52:55], v[192:195], v[160:163], v[52:55]
	v_mfma_f32_16x16x32_bf16 v[48:51], v[200:203], v[160:163], v[48:51]
	v_mfma_f32_16x16x32_bf16 v[36:39], v[192:195], v[168:171], v[36:39]
	v_mfma_f32_16x16x32_bf16 v[32:35], v[200:203], v[168:171], v[32:35]
	v_mfma_f32_16x16x32_bf16 v[20:23], v[192:195], v[176:179], v[20:23]
	v_mfma_f32_16x16x32_bf16 v[16:19], v[200:203], v[176:179], v[16:19]
	v_mfma_f32_16x16x32_bf16 v[4:7], v[192:195], v[184:187], v[4:7]
	v_mfma_f32_16x16x32_bf16 v[0:3], v[200:203], v[184:187], v[0:3]
	v_mfma_f32_16x16x32_bf16 v[52:55], v[196:199], v[164:167], v[52:55]
	v_mfma_f32_16x16x32_bf16 v[48:51], v[204:207], v[164:167], v[48:51]
	v_mfma_f32_16x16x32_bf16 v[36:39], v[196:199], v[172:175], v[36:39]
	v_mfma_f32_16x16x32_bf16 v[32:35], v[204:207], v[172:175], v[32:35]
	v_mfma_f32_16x16x32_bf16 v[20:23], v[196:199], v[180:183], v[20:23]
	v_mfma_f32_16x16x32_bf16 v[16:19], v[204:207], v[180:183], v[16:19]
	v_mfma_f32_16x16x32_bf16 v[4:7], v[196:199], v[188:191], v[4:7]
	v_mfma_f32_16x16x32_bf16 v[0:3], v[204:207], v[188:191], v[0:3]
	s_setprio 0
	s_add_i32 s0, s88, 0x100
	v_add_u32_e32 v142, s0, v150
	s_barrier
	ds_read_b128 v[134:137], v142
	ds_read_b128 v[138:141], v142 offset:1024
	ds_read_b128 v[152:155], v142 offset:2048
	ds_read_b128 v[156:159], v142 offset:3072
	s_add_u32 s10, s74, 0x80000
	s_addc_u32 s11, s75, 0
	s_mov_b32 m0, s25
	v_lshl_add_u64 v[142:143], s[10:11], 0, v[128:129]
	ds_read_b128 v[160:163], v151 offset:32768
	ds_read_b128 v[164:167], v151 offset:33792
	ds_read_b128 v[168:171], v151 offset:34816
	ds_read_b128 v[172:175], v151 offset:35840
	ds_read_b128 v[176:179], v151 offset:36864
	ds_read_b128 v[180:183], v151 offset:37888
	ds_read_b128 v[184:187], v151 offset:38912
	ds_read_b128 v[188:191], v151 offset:39936
	global_load_lds_dwordx4 v[142:143], off
	v_lshl_add_u64 v[142:143], s[10:11], 0, v[130:131]
	s_mov_b32 m0, s36
	s_nop 0
	global_load_lds_dwordx4 v[142:143], off
	s_waitcnt lgkmcnt(8)
	s_barrier
	s_waitcnt lgkmcnt(0)
	s_setprio 1
	s_waitcnt lgkmcnt(0)
	v_mfma_f32_16x16x32_bf16 v[124:127], v[134:137], v[160:163], v[124:127]
	v_mfma_f32_16x16x32_bf16 v[120:123], v[152:155], v[160:163], v[120:123]
	v_mfma_f32_16x16x32_bf16 v[108:111], v[134:137], v[168:171], v[108:111]
	v_mfma_f32_16x16x32_bf16 v[104:107], v[152:155], v[168:171], v[104:107]
	v_mfma_f32_16x16x32_bf16 v[92:95], v[134:137], v[176:179], v[92:95]
	v_mfma_f32_16x16x32_bf16 v[88:91], v[152:155], v[176:179], v[88:91]
	v_mfma_f32_16x16x32_bf16 v[76:79], v[134:137], v[184:187], v[76:79]
	v_mfma_f32_16x16x32_bf16 v[72:75], v[152:155], v[184:187], v[72:75]
	v_mfma_f32_16x16x32_bf16 v[124:127], v[138:141], v[164:167], v[124:127]
	v_mfma_f32_16x16x32_bf16 v[120:123], v[156:159], v[164:167], v[120:123]
	v_mfma_f32_16x16x32_bf16 v[108:111], v[138:141], v[172:175], v[108:111]
	v_mfma_f32_16x16x32_bf16 v[104:107], v[156:159], v[172:175], v[104:107]
	v_mfma_f32_16x16x32_bf16 v[92:95], v[138:141], v[180:183], v[92:95]
	v_mfma_f32_16x16x32_bf16 v[88:91], v[156:159], v[180:183], v[88:91]
	v_mfma_f32_16x16x32_bf16 v[76:79], v[138:141], v[188:191], v[76:79]
	v_mfma_f32_16x16x32_bf16 v[72:75], v[156:159], v[188:191], v[72:75]
	s_setprio 0
	s_barrier
	s_add_i32 s1, s89, 0x100
	v_add_u32_e32 v142, s1, v150
	s_add_i32 s0, s0, s5
	ds_read_b128 v[192:195], v142
	ds_read_b128 v[196:199], v142 offset:1024
	ds_read_b128 v[200:203], v142 offset:2048
	ds_read_b128 v[204:207], v142 offset:3072
	v_lshl_add_u64 v[142:143], s[70:71], 0, v[146:147]
	s_mov_b32 m0, s0
	s_nop 0
	global_load_lds_dwordx4 v[142:143], off
	v_lshl_add_u64 v[142:143], s[70:71], 0, v[132:133]
	s_add_i32 m0, s0, 0x2000
	s_nop 0
	global_load_lds_dwordx4 v[142:143], off
	s_barrier
	s_waitcnt lgkmcnt(0)
	s_setprio 1
	s_waitcnt lgkmcnt(0)
	v_mfma_f32_16x16x32_bf16 v[116:119], v[192:195], v[160:163], v[116:119]
	v_mfma_f32_16x16x32_bf16 v[112:115], v[200:203], v[160:163], v[112:115]
	v_mfma_f32_16x16x32_bf16 v[100:103], v[192:195], v[168:171], v[100:103]
	v_mfma_f32_16x16x32_bf16 v[96:99], v[200:203], v[168:171], v[96:99]
	v_mfma_f32_16x16x32_bf16 v[84:87], v[192:195], v[176:179], v[84:87]
	v_mfma_f32_16x16x32_bf16 v[80:83], v[200:203], v[176:179], v[80:83]
	v_mfma_f32_16x16x32_bf16 v[68:71], v[192:195], v[184:187], v[68:71]
	v_mfma_f32_16x16x32_bf16 v[64:67], v[200:203], v[184:187], v[64:67]
	v_mfma_f32_16x16x32_bf16 v[116:119], v[196:199], v[164:167], v[116:119]
	v_mfma_f32_16x16x32_bf16 v[112:115], v[204:207], v[164:167], v[112:115]
	v_mfma_f32_16x16x32_bf16 v[100:103], v[196:199], v[172:175], v[100:103]
	v_mfma_f32_16x16x32_bf16 v[96:99], v[204:207], v[172:175], v[96:99]
	v_mfma_f32_16x16x32_bf16 v[84:87], v[196:199], v[180:183], v[84:87]
	v_mfma_f32_16x16x32_bf16 v[80:83], v[204:207], v[180:183], v[80:83]
	v_mfma_f32_16x16x32_bf16 v[68:71], v[196:199], v[188:191], v[68:71]
	v_mfma_f32_16x16x32_bf16 v[64:67], v[204:207], v[188:191], v[64:67]
	s_setprio 0
	s_mov_b32 m0, s45
	v_lshl_add_u64 v[142:143], s[72:73], 0, v[128:129]
	s_barrier
; DI unsigned pk2(float lo, float hi) { unsigned r; asm("v_cvt_pk_bf16_f32 %0, %1, %2" : "=v"(r) : "v"(lo), "v"(hi)); return r; }
; #define G_STAGE(bufoff, gbase, voff) do { _Pragma("unroll") for (int _i = 0; _i < 2; ++_i) \
;         __builtin_amdgcn_global_load_lds((const unsigned*)((const char*)(gbase) + (voff)[_i]), (LAS unsigned*)(lds + (bufoff) + ldsw + _i * 8192), 16, 0, 0); } while (0)
; #define G_LDA(dst, b, h) do { _Pragma("unroll") for (int m = 0; m < 4; ++m) _Pragma("unroll") for (int k = 0; k < 2; ++k) dst[m][k] = *(const LAS bf16x8*)(lds + G_SA(b, h) + aoff + m * 2048 + k * 1024); } while (0)
; #define G_MMA(ai, bj, At, Bt) do { __builtin_amdgcn_s_setprio(1); _Pragma("unroll") for (int m = 0; m < 4; ++m) _Pragma("unroll") for (int n = 0; n < 2; ++n) _Pragma("unroll") for (int k = 0; k < 2; ++k) \
;         acc[ai][bj][m][n] = __builtin_amdgcn_mfma_f32_16x16x32_bf16(Bt[n][k], At[m][k], acc[ai][bj][m][n], 0, 0, 0); __builtin_amdgcn_s_setprio(0); } while (0)
; #define G_WAIT_V(n) asm volatile("s_waitcnt vmcnt(" #n ")" ::: "memory")
; #define G_WAIT_L(n) asm volatile("s_waitcnt lgkmcnt(" #n ")" ::: "memory")
; #define G_BAR __builtin_amdgcn_s_barrier()
; #define G_SCHED __builtin_amdgcn_sched_barrier(0)
; template <class J>
; DI void gemm_phase(LAS unsigned char* lds, const J& job) {
;     ...
;       G_LDA(At, 1, 1); G_STAGE(G_SA(1, 0), a3, voffA);
;       G_BAR; G_WAIT_L(0); G_MMA(1, 0, At, B0); G_BAR; G_SCHED;
;       G_STAGE(G_SB(1, 1), b3 + hstepB, voffB);
;       G_WAIT_V(6); G_BAR; G_MMA(1, 1, At, B1); G_BAR;
;   DI void epi(const Acc& acc, const Unit& u, int wr, int wc, int fr, int fq) const {
;     ...
;         const int rl = ai * HALF + wr * 64 + m * 16 + fr;
; #pragma unroll
;         for (int bj = 0; bj < 2; ++bj) {
;           const int col = u.pn * 256 + bj * HALF + wc * 32 + 8 * fq;
;           const f32x4 v0 = acc[ai][bj][m][0], v1 = acc[ai][bj][m][1];
;           const int row = u.pm * 256 + rl;
;           u32x4 o; o.x = pk2(v0.x, v0.y); o.y = pk2(v0.z, v0.w); o.z = pk2(v1.x, v1.y); o.w = pk2(v1.z, v1.w);
;           *(u32x4*)(proj + (size_t)row * NPROJ + col) = o;
;           if (u.pn >= 8 && u.pn < 12) {
;             const int isv = u.pn >= 10; const int cc = col - (isv ? C_BV : C_BK);
;             float* dst = out + (isv ? O_VP : O_KP) + ((size_t)l * TP + row) * 512 + cc;
;             *(f32x4*)dst = v0; *(f32x4*)(dst + 4) = v1;
;           }
	ds_read_b128 v[160:163], v151 offset:49152
	ds_read_b128 v[164:167], v151 offset:50176
	ds_read_b128 v[168:171], v151 offset:51200
	ds_read_b128 v[172:175], v151 offset:52224
	ds_read_b128 v[176:179], v151 offset:53248
	ds_read_b128 v[180:183], v151 offset:54272
	ds_read_b128 v[184:187], v151 offset:55296
	ds_read_b128 v[188:191], v151 offset:56320
	global_load_lds_dwordx4 v[142:143], off
	v_lshl_add_u64 v[142:143], s[72:73], 0, v[130:131]
	s_mov_b32 m0, s65
	s_nop 0
	global_load_lds_dwordx4 v[142:143], off
	s_barrier
	s_waitcnt lgkmcnt(0)
	s_setprio 1
	s_waitcnt lgkmcnt(0)
	v_mfma_f32_16x16x32_bf16 v[60:63], v[134:137], v[160:163], v[60:63]
	v_mfma_f32_16x16x32_bf16 v[56:59], v[152:155], v[160:163], v[56:59]
	v_mfma_f32_16x16x32_bf16 v[44:47], v[134:137], v[168:171], v[44:47]
	v_mfma_f32_16x16x32_bf16 v[40:43], v[152:155], v[168:171], v[40:43]
	v_mfma_f32_16x16x32_bf16 v[28:31], v[134:137], v[176:179], v[28:31]
	v_mfma_f32_16x16x32_bf16 v[24:27], v[152:155], v[176:179], v[24:27]
	v_mfma_f32_16x16x32_bf16 v[12:15], v[134:137], v[184:187], v[12:15]
	v_mfma_f32_16x16x32_bf16 v[8:11], v[152:155], v[184:187], v[8:11]
	v_mfma_f32_16x16x32_bf16 v[60:63], v[138:141], v[164:167], v[60:63]
	v_mfma_f32_16x16x32_bf16 v[56:59], v[156:159], v[164:167], v[56:59]
	v_mfma_f32_16x16x32_bf16 v[44:47], v[138:141], v[172:175], v[44:47]
	v_mfma_f32_16x16x32_bf16 v[40:43], v[156:159], v[172:175], v[40:43]
	v_mfma_f32_16x16x32_bf16 v[28:31], v[138:141], v[180:183], v[28:31]
	v_mfma_f32_16x16x32_bf16 v[24:27], v[156:159], v[180:183], v[24:27]
	v_mfma_f32_16x16x32_bf16 v[12:15], v[138:141], v[188:191], v[12:15]
	v_mfma_f32_16x16x32_bf16 v[8:11], v[156:159], v[188:191], v[8:11]
	s_setprio 0
	s_barrier
	s_add_u32 s10, s70, 0x80000
	s_addc_u32 s11, s71, 0
	s_add_i32 s0, s1, s5
	v_lshl_add_u64 v[134:135], s[10:11], 0, v[146:147]
	s_mov_b32 m0, s0
	s_nop 0
	global_load_lds_dwordx4 v[134:135], off
	v_lshl_add_u64 v[134:135], s[10:11], 0, v[132:133]
	s_add_i32 m0, s0, 0x2000
	s_nop 0
	global_load_lds_dwordx4 v[134:135], off
	s_waitcnt vmcnt(6)
	s_barrier
	s_setprio 1
	v_mfma_f32_16x16x32_bf16 v[52:55], v[192:195], v[160:163], v[52:55]
	v_mfma_f32_16x16x32_bf16 v[48:51], v[200:203], v[160:163], v[48:51]
	v_mfma_f32_16x16x32_bf16 v[36:39], v[192:195], v[168:171], v[36:39]
	v_mfma_f32_16x16x32_bf16 v[32:35], v[200:203], v[168:171], v[32:35]
	v_mfma_f32_16x16x32_bf16 v[20:23], v[192:195], v[176:179], v[20:23]
	v_mfma_f32_16x16x32_bf16 v[16:19], v[200:203], v[176:179], v[16:19]
	v_mfma_f32_16x16x32_bf16 v[4:7], v[192:195], v[184:187], v[4:7]
	v_mfma_f32_16x16x32_bf16 v[0:3], v[200:203], v[184:187], v[0:3]
	v_mfma_f32_16x16x32_bf16 v[52:55], v[196:199], v[164:167], v[52:55]
	v_mfma_f32_16x16x32_bf16 v[48:51], v[204:207], v[164:167], v[48:51]
	v_mfma_f32_16x16x32_bf16 v[36:39], v[196:199], v[172:175], v[36:39]
	v_mfma_f32_16x16x32_bf16 v[32:35], v[204:207], v[172:175], v[32:35]
	v_mfma_f32_16x16x32_bf16 v[20:23], v[196:199], v[180:183], v[20:23]
	v_mfma_f32_16x16x32_bf16 v[16:19], v[204:207], v[180:183], v[16:19]
	v_mfma_f32_16x16x32_bf16 v[4:7], v[196:199], v[188:191], v[4:7]
	v_mfma_f32_16x16x32_bf16 v[0:3], v[204:207], v[188:191], v[0:3]
	s_setprio 0
	s_add_i32 s6, s6, 2
	s_addk_i32 s56, 0x100
	s_addk_i32 s7, 0x100
	s_add_i32 s1, s56, 0xffffff80
	s_and_b32 s0, s7, 0xf80
	s_and_b32 s1, s1, 0xf00
	s_add_u32 s10, s68, s1
	s_addc_u32 s11, s69, 0
	s_add_u32 s1, s66, s1
	s_addc_u32 s57, s67, 0
	s_and_b32 s70, s56, 0xf80
	s_add_u32 s71, s68, s70
	s_addc_u32 s72, s69, 0
	s_add_u32 s70, s66, s70
	s_addc_u32 s80, s67, 0
	s_cmp_eq_u32 s6, 28
	s_cselect_b32 s75, s46, s11
	s_cselect_b32 s74, s21, s10
	s_cselect_b32 s77, s96, s57
	s_cselect_b32 s76, s47, s1
	s_cselect_b32 s73, s97, s72
	s_cselect_b32 s72, s33, s71
	s_cselect_b32 s71, vcc_hi, s80
	s_cselect_b32 s70, vcc_lo, s70
	s_cmp_gt_u32 s6, 29
	s_barrier
	s_cbranch_scc0 .LBB0_282
	v_mov_b32_e32 v135, v148
	v_mov_b32_e32 v134, v149
	s_lshl_b32 s0, s64, 8
	s_or_b32 s0, s0, s38
	v_lshl_add_u32 v134, v134, 3, s0
	s_lshl_b32 s0, s8, 8
	s_add_i32 s0, s0, s37
	v_add_u32_e32 v136, s0, v135
	s_and_b32 s0, s64, -4
	s_cmp_eq_u32 s0, 8
	s_cselect_b64 s[66:67], -1, 0
	s_cmp_gt_u32 s64, 9
	s_cselect_b64 s[6:7], -1, 0
	s_and_b64 s[6:7], s[6:7], exec
	s_movk_i32 s1, 0xf600
	v_mov_b64_e32 v[138:139], s[26:27]
	s_cselect_b32 s7, s1, 0xfffff800
	s_mov_b32 s1, 0x3040000
	v_ashrrev_i32_e32 v137, 31, v136
	v_mad_i64_i32 v[138:139], s[8:9], v136, s92, v[138:139]
	v_ashrrev_i32_e32 v135, 31, v134
	s_cselect_b32 s6, s1, 0x2040000
	s_cmp_lg_u32 s0, 8
	v_lshlrev_b64 v[140:141], 11, v[136:137]
	v_lshl_add_u64 v[142:143], v[134:135], 1, v[138:139]
	v_add_u32_e32 v138, s7, v134
	v_cvt_pk_bf16_f32 v152, v124, v125
	v_cvt_pk_bf16_f32 v153, v126, v127
	v_cvt_pk_bf16_f32 v154, v120, v121
	v_cvt_pk_bf16_f32 v155, v122, v123
	global_store_dwordx4 v[142:143], v[152:155], off
	s_cbranch_scc1 .LBB0_285
	s_lshl_b32 s0, s6, 2
	s_add_u32 s8, s83, s0
	s_addc_u32 s9, s86, 0
	v_lshl_add_u64 v[152:153], s[8:9], 0, v[140:141]
	v_ashrrev_i32_e32 v139, 31, v138
	v_lshl_add_u64 v[152:153], v[138:139], 2, v[152:153]
	global_store_dwordx4 v[152:153], v[124:127], off
	global_store_dwordx4 v[152:153], v[120:123], off offset:16
